# residual epilogues: lane^16 / lane^32 reduction hops via v_permlane16/32_swap instead of ds_bpermute (64 hops) on v27
# speedup vs baseline: 1.0016x; 1.0009x over previous
.LBB0_736:
	s_lshl_b32 s14, s14, 8
	v_mov_b32_e32 v166, v149
	v_mov_b32_e32 v167, v148
	s_add_i32 s14, s14, s61
	s_lshl_b32 s22, s12, 8
	v_add_u32_e32 v146, s14, v166
	s_or_b32 s22, s22, s62
	v_ashrrev_i32_e32 v147, 31, v146
	v_lshl_add_u32 v144, v167, 3, s22
	v_lshlrev_b64 v[154:155], 11, v[146:147]
	v_ashrrev_i32_e32 v145, 31, v144
	v_lshl_add_u64 v[154:155], s[18:19], 0, v[154:155]
	v_lshl_add_u64 v[158:159], v[144:145], 1, v[154:155]
	v_mov_b32_e32 v236, 0x8000
	v_mov_b32_e32 v237, 0
	v_mov_b32_e32 v238, 0x28000
	v_mov_b32_e32 v239, 0
	global_load_dwordx4 v[168:171], v[158:159], off
	global_load_dwordx4 v[172:175], v[158:159], off offset:256
	v_lshl_add_u64 v[234:235], v[158:159], 0, v[236:237]
	global_load_dwordx4 v[176:179], v[234:235], off
	global_load_dwordx4 v[180:183], v[234:235], off offset:256
	v_lshl_add_u64 v[234:235], v[234:235], 0, v[236:237]
	global_load_dwordx4 v[184:187], v[234:235], off
	global_load_dwordx4 v[188:191], v[234:235], off offset:256
	v_lshl_add_u64 v[234:235], v[234:235], 0, v[236:237]
	global_load_dwordx4 v[192:195], v[234:235], off
	global_load_dwordx4 v[196:199], v[234:235], off offset:256
	v_lshl_add_u64 v[234:235], v[234:235], 0, v[238:239]
	global_load_dwordx4 v[200:203], v[234:235], off
	global_load_dwordx4 v[204:207], v[234:235], off offset:256
	v_lshl_add_u64 v[234:235], v[234:235], 0, v[236:237]
	global_load_dwordx4 v[208:211], v[234:235], off
	global_load_dwordx4 v[212:215], v[234:235], off offset:256
	v_lshl_add_u64 v[234:235], v[234:235], 0, v[236:237]
	global_load_dwordx4 v[216:219], v[234:235], off
	global_load_dwordx4 v[220:223], v[234:235], off offset:256
	v_lshl_add_u64 v[234:235], v[234:235], 0, v[236:237]
	global_load_dwordx4 v[226:229], v[234:235], off
	global_load_dwordx4 v[230:233], v[234:235], off offset:256
	v_cmp_eq_u32_e32 vcc, 0, v167
	s_waitcnt vmcnt(15)
	v_mov_b32_e32 v154, v168
	v_mov_b32_e32 v155, v169
	v_mov_b32_e32 v156, v170
	v_mov_b32_e32 v157, v171
	v_lshlrev_b32_e32 v160, 16, v154
	v_and_b32_e32 v161, 0xffff0000, v154
	v_lshlrev_b32_e32 v154, 16, v155
	v_and_b32_e32 v155, 0xffff0000, v155
	v_lshlrev_b32_e32 v162, 16, v156
	v_and_b32_e32 v163, 0xffff0000, v156
	v_lshlrev_b32_e32 v156, 16, v157
	v_and_b32_e32 v157, 0xffff0000, v157
	v_pk_add_f32 v[126:127], v[126:127], v[154:155]
	v_pk_add_f32 v[160:161], v[124:125], v[160:161]
	v_pk_add_f32 v[164:165], v[122:123], v[156:157]
	v_pk_add_f32 v[162:163], v[120:121], v[162:163]
	v_cvt_pk_bf16_f32 v122, v160, v161
	v_cvt_pk_bf16_f32 v123, v126, v127
	v_mul_f32_e32 v161, v161, v161
	v_cvt_pk_bf16_f32 v124, v162, v163
	v_cvt_pk_bf16_f32 v125, v164, v165
	v_mul_f32_e32 v127, v127, v127
	v_mul_f32_e32 v163, v163, v163
	v_mul_f32_e32 v165, v165, v165
	v_fmac_f32_e32 v161, v160, v160
	v_fmac_f32_e32 v127, v126, v126
	v_fmac_f32_e32 v163, v162, v162
	v_fmac_f32_e32 v165, v164, v164
	v_add_f32_e32 v126, v161, v127
	v_add_f32_e32 v127, v163, v165
	v_add_f32_e32 v162, v126, v127
	v_lshlrev_b32_e32 v120, 2, v166
	v_lshl_add_u32 v121, v167, 6, v120
	v_xor_b32_e32 v120, 64, v121
	global_store_dwordx4 v[158:159], v[122:125], off
	s_waitcnt vmcnt(15)
	v_mov_b32_e32 v154, v172
	v_mov_b32_e32 v155, v173
	v_mov_b32_e32 v156, v174
	v_mov_b32_e32 v157, v175
	v_lshlrev_b32_e32 v126, 16, v154
	v_and_b32_e32 v127, 0xffff0000, v154
	v_lshlrev_b32_e32 v154, 16, v155
	v_and_b32_e32 v155, 0xffff0000, v155
	v_lshlrev_b32_e32 v160, 16, v156
	v_and_b32_e32 v161, 0xffff0000, v156
	v_lshlrev_b32_e32 v156, 16, v157
	v_and_b32_e32 v157, 0xffff0000, v157
	v_pk_add_f32 v[118:119], v[118:119], v[154:155]
	v_pk_add_f32 v[116:117], v[116:117], v[126:127]
	v_pk_add_f32 v[126:127], v[114:115], v[156:157]
	v_pk_add_f32 v[154:155], v[112:113], v[160:161]
	v_mul_f32_e32 v112, v117, v117
	v_mul_f32_e32 v113, v119, v119
	v_mul_f32_e32 v114, v155, v155
	v_mul_f32_e32 v115, v127, v127
	v_fmac_f32_e32 v112, v116, v116
	v_fmac_f32_e32 v113, v118, v118
	v_fmac_f32_e32 v114, v154, v154
	v_fmac_f32_e32 v115, v126, v126
	v_add_f32_e32 v112, v112, v113
	v_add_f32_e32 v113, v114, v115
	v_add_f32_e32 v112, v112, v113
	v_add_f32_e32 v112, v162, v112
	v_mov_b32_e32 v113, v112
	s_nop 1
	v_permlane16_swap_b32_e32 v112, v113
	v_xor_b32_e32 v114, 0x80, v121
	v_cvt_pk_bf16_f32 v116, v116, v117
	v_cvt_pk_bf16_f32 v117, v118, v119
	v_cvt_pk_bf16_f32 v118, v154, v155
	s_waitcnt lgkmcnt(0)
	v_add_f32_e32 v112, v112, v113
	v_mov_b32_e32 v113, v112
	s_nop 1
	v_permlane32_swap_b32_e32 v112, v113
	v_cvt_pk_bf16_f32 v119, v126, v127
	global_store_dwordx4 v[158:159], v[116:119], off offset:256
	s_and_saveexec_b64 s[46:47], vcc
	s_cbranch_execz .LBB0_738
	s_waitcnt lgkmcnt(0)
	v_add_f32_e32 v115, v112, v113
	s_lshl_b32 s26, s12, 2
	v_lshlrev_b64 v[112:113], 6, v[146:147]
	s_ashr_i32 s27, s26, 31
	v_lshl_add_u64 v[112:113], s[10:11], 0, v[112:113]
	v_lshl_add_u64 v[112:113], s[26:27], 2, v[112:113]
	s_lshl_b32 s14, s60, 2
	v_lshl_add_u64 v[112:113], v[112:113], 0, s[14:15]
	global_store_dword v[112:113], v115, off
.LBB0_738:
	s_or_b64 exec, exec, s[46:47]
	v_add_u32_e32 v112, 16, v146
	s_waitcnt lgkmcnt(0)
	v_ashrrev_i32_e32 v113, 31, v112
	v_lshlrev_b64 v[116:117], 11, v[112:113]
	v_lshl_add_u64 v[116:117], s[18:19], 0, v[116:117]
	v_lshl_add_u64 v[122:123], v[144:145], 1, v[116:117]
	s_waitcnt vmcnt(16)
	v_mov_b32_e32 v116, v176
	v_mov_b32_e32 v117, v177
	v_mov_b32_e32 v118, v178
	v_mov_b32_e32 v119, v179
	v_lshlrev_b32_e32 v124, 16, v116
	v_and_b32_e32 v125, 0xffff0000, v116
	v_lshlrev_b32_e32 v116, 16, v117
	v_and_b32_e32 v117, 0xffff0000, v117
	v_lshlrev_b32_e32 v126, 16, v118
	v_and_b32_e32 v127, 0xffff0000, v118
	v_lshlrev_b32_e32 v118, 16, v119
	v_and_b32_e32 v119, 0xffff0000, v119
	v_pk_add_f32 v[116:117], v[110:111], v[116:117]
	v_pk_add_f32 v[124:125], v[108:109], v[124:125]
	v_pk_add_f32 v[118:119], v[106:107], v[118:119]
	v_pk_add_f32 v[126:127], v[104:105], v[126:127]
	v_cvt_pk_bf16_f32 v104, v124, v125
	v_cvt_pk_bf16_f32 v105, v116, v117
	v_mul_f32_e32 v115, v125, v125
	v_cvt_pk_bf16_f32 v106, v126, v127
	v_cvt_pk_bf16_f32 v107, v118, v119
	v_mul_f32_e32 v117, v117, v117
	v_mul_f32_e32 v121, v127, v127
	v_mul_f32_e32 v119, v119, v119
	v_fmac_f32_e32 v115, v124, v124
	v_fmac_f32_e32 v117, v116, v116
	v_fmac_f32_e32 v121, v126, v126
	v_fmac_f32_e32 v119, v118, v118
	v_add_f32_e32 v115, v115, v117
	v_add_f32_e32 v116, v121, v119
	v_add_f32_e32 v115, v115, v116
	global_store_dwordx4 v[122:123], v[104:107], off
	s_waitcnt vmcnt(16)
	v_mov_b32_e32 v108, v180
	v_mov_b32_e32 v109, v181
	v_mov_b32_e32 v110, v182
	v_mov_b32_e32 v111, v183
	v_lshlrev_b32_e32 v116, 16, v108
	v_and_b32_e32 v117, 0xffff0000, v108
	v_lshlrev_b32_e32 v108, 16, v109
	v_and_b32_e32 v109, 0xffff0000, v109
	v_lshlrev_b32_e32 v118, 16, v110
	v_and_b32_e32 v119, 0xffff0000, v110
	v_lshlrev_b32_e32 v110, 16, v111
	v_and_b32_e32 v111, 0xffff0000, v111
	v_pk_add_f32 v[102:103], v[102:103], v[108:109]
	v_pk_add_f32 v[100:101], v[100:101], v[116:117]
	v_pk_add_f32 v[108:109], v[98:99], v[110:111]
	v_pk_add_f32 v[110:111], v[96:97], v[118:119]
	v_mul_f32_e32 v96, v101, v101
	v_mul_f32_e32 v97, v103, v103
	v_mul_f32_e32 v98, v111, v111
	v_mul_f32_e32 v99, v109, v109
	v_fmac_f32_e32 v96, v100, v100
	v_fmac_f32_e32 v97, v102, v102
	v_fmac_f32_e32 v98, v110, v110
	v_fmac_f32_e32 v99, v108, v108
	v_add_f32_e32 v96, v96, v97
	v_add_f32_e32 v97, v98, v99
	v_add_f32_e32 v96, v96, v97
	v_add_f32_e32 v96, v115, v96
	v_mov_b32_e32 v97, v96
	s_nop 1
	v_permlane16_swap_b32_e32 v96, v97
	v_cvt_pk_bf16_f32 v98, v100, v101
	v_cvt_pk_bf16_f32 v99, v102, v103
	v_cvt_pk_bf16_f32 v100, v110, v111
	v_cvt_pk_bf16_f32 v101, v108, v109
	s_waitcnt lgkmcnt(0)
	v_add_f32_e32 v96, v96, v97
	v_mov_b32_e32 v97, v96
	s_nop 1
	v_permlane32_swap_b32_e32 v96, v97
	global_store_dwordx4 v[122:123], v[98:101], off offset:256
	s_and_saveexec_b64 s[46:47], vcc
	s_cbranch_execz .LBB0_740
	s_waitcnt lgkmcnt(0)
	v_add_f32_e32 v98, v96, v97
	s_lshl_b32 s26, s12, 2
	v_lshlrev_b64 v[96:97], 6, v[112:113]
	s_ashr_i32 s27, s26, 31
	v_lshl_add_u64 v[96:97], s[10:11], 0, v[96:97]
	v_lshl_add_u64 v[96:97], s[26:27], 2, v[96:97]
	s_lshl_b32 s14, s60, 2
	v_lshl_add_u64 v[96:97], v[96:97], 0, s[14:15]
	global_store_dword v[96:97], v98, off
.LBB0_740:
	s_or_b64 exec, exec, s[46:47]
	v_add_u32_e32 v96, 32, v146
	s_waitcnt lgkmcnt(0)
	v_ashrrev_i32_e32 v97, 31, v96
	v_lshlrev_b64 v[98:99], 11, v[96:97]
	v_lshl_add_u64 v[98:99], s[18:19], 0, v[98:99]
	v_lshl_add_u64 v[102:103], v[144:145], 1, v[98:99]
	s_waitcnt vmcnt(17)
	v_mov_b32_e32 v98, v184
	v_mov_b32_e32 v99, v185
	v_mov_b32_e32 v100, v186
	v_mov_b32_e32 v101, v187
	v_lshlrev_b32_e32 v104, 16, v98
	v_and_b32_e32 v105, 0xffff0000, v98
	v_lshlrev_b32_e32 v98, 16, v99
	v_and_b32_e32 v99, 0xffff0000, v99
	v_lshlrev_b32_e32 v106, 16, v100
	v_and_b32_e32 v107, 0xffff0000, v100
	v_lshlrev_b32_e32 v100, 16, v101
	v_and_b32_e32 v101, 0xffff0000, v101
	v_pk_add_f32 v[98:99], v[94:95], v[98:99]
	v_pk_add_f32 v[104:105], v[92:93], v[104:105]
	v_pk_add_f32 v[100:101], v[90:91], v[100:101]
	v_pk_add_f32 v[106:107], v[88:89], v[106:107]
	v_cvt_pk_bf16_f32 v88, v104, v105
	v_cvt_pk_bf16_f32 v89, v98, v99
	v_mul_f32_e32 v105, v105, v105
	v_cvt_pk_bf16_f32 v90, v106, v107
	v_cvt_pk_bf16_f32 v91, v100, v101
	v_mul_f32_e32 v99, v99, v99
	v_mul_f32_e32 v107, v107, v107
	v_mul_f32_e32 v101, v101, v101
	v_fmac_f32_e32 v105, v104, v104
	v_fmac_f32_e32 v99, v98, v98
	v_fmac_f32_e32 v107, v106, v106
	v_fmac_f32_e32 v101, v100, v100
	v_add_f32_e32 v98, v105, v99
	v_add_f32_e32 v99, v107, v101
	v_add_f32_e32 v104, v98, v99
	global_store_dwordx4 v[102:103], v[88:91], off
	s_waitcnt vmcnt(17)
	v_mov_b32_e32 v92, v188
	v_mov_b32_e32 v93, v189
	v_mov_b32_e32 v94, v190
	v_mov_b32_e32 v95, v191
	v_lshlrev_b32_e32 v98, 16, v92
	v_and_b32_e32 v99, 0xffff0000, v92
	v_lshlrev_b32_e32 v92, 16, v93
	v_and_b32_e32 v93, 0xffff0000, v93
	v_lshlrev_b32_e32 v100, 16, v94
	v_and_b32_e32 v101, 0xffff0000, v94
	v_lshlrev_b32_e32 v94, 16, v95
	v_and_b32_e32 v95, 0xffff0000, v95
	v_pk_add_f32 v[86:87], v[86:87], v[92:93]
	v_pk_add_f32 v[84:85], v[84:85], v[98:99]
	v_pk_add_f32 v[92:93], v[82:83], v[94:95]
	v_pk_add_f32 v[94:95], v[80:81], v[100:101]
	v_mul_f32_e32 v80, v85, v85
	v_mul_f32_e32 v81, v87, v87
	v_mul_f32_e32 v82, v95, v95
	v_mul_f32_e32 v83, v93, v93
	v_fmac_f32_e32 v80, v84, v84
	v_fmac_f32_e32 v81, v86, v86
	v_fmac_f32_e32 v82, v94, v94
	v_fmac_f32_e32 v83, v92, v92
	v_add_f32_e32 v80, v80, v81
	v_add_f32_e32 v81, v82, v83
	v_add_f32_e32 v80, v80, v81
	v_add_f32_e32 v80, v104, v80
	v_mov_b32_e32 v81, v80
	s_nop 1
	v_permlane16_swap_b32_e32 v80, v81
	v_cvt_pk_bf16_f32 v82, v84, v85
	v_cvt_pk_bf16_f32 v83, v86, v87
	v_cvt_pk_bf16_f32 v84, v94, v95
	v_cvt_pk_bf16_f32 v85, v92, v93
	s_waitcnt lgkmcnt(0)
	v_add_f32_e32 v80, v80, v81
	v_mov_b32_e32 v81, v80
	s_nop 1
	v_permlane32_swap_b32_e32 v80, v81
	global_store_dwordx4 v[102:103], v[82:85], off offset:256
	s_and_saveexec_b64 s[46:47], vcc
	s_cbranch_execz .LBB0_742
	s_waitcnt lgkmcnt(0)
	v_add_f32_e32 v82, v80, v81
	s_lshl_b32 s26, s12, 2
	v_lshlrev_b64 v[80:81], 6, v[96:97]
	s_ashr_i32 s27, s26, 31
	v_lshl_add_u64 v[80:81], s[10:11], 0, v[80:81]
	v_lshl_add_u64 v[80:81], s[26:27], 2, v[80:81]
	s_lshl_b32 s14, s60, 2
	v_lshl_add_u64 v[80:81], v[80:81], 0, s[14:15]
	global_store_dword v[80:81], v82, off
.LBB0_742:
	s_or_b64 exec, exec, s[46:47]
	v_add_u32_e32 v80, 48, v146
	s_waitcnt lgkmcnt(0)
	v_ashrrev_i32_e32 v81, 31, v80
	v_lshlrev_b64 v[82:83], 11, v[80:81]
	v_lshl_add_u64 v[82:83], s[18:19], 0, v[82:83]
	v_lshl_add_u64 v[86:87], v[144:145], 1, v[82:83]
	s_waitcnt vmcnt(18)
	v_mov_b32_e32 v82, v192
	v_mov_b32_e32 v83, v193
	v_mov_b32_e32 v84, v194
	v_mov_b32_e32 v85, v195
	v_lshlrev_b32_e32 v88, 16, v82
	v_and_b32_e32 v89, 0xffff0000, v82
	v_lshlrev_b32_e32 v82, 16, v83
	v_and_b32_e32 v83, 0xffff0000, v83
	v_lshlrev_b32_e32 v90, 16, v84
	v_and_b32_e32 v91, 0xffff0000, v84
	v_lshlrev_b32_e32 v84, 16, v85
	v_and_b32_e32 v85, 0xffff0000, v85
	v_pk_add_f32 v[82:83], v[78:79], v[82:83]
	v_pk_add_f32 v[88:89], v[76:77], v[88:89]
	v_pk_add_f32 v[84:85], v[74:75], v[84:85]
	v_pk_add_f32 v[90:91], v[72:73], v[90:91]
	v_cvt_pk_bf16_f32 v72, v88, v89
	v_cvt_pk_bf16_f32 v73, v82, v83
	v_mul_f32_e32 v89, v89, v89
	v_cvt_pk_bf16_f32 v74, v90, v91
	v_cvt_pk_bf16_f32 v75, v84, v85
	v_mul_f32_e32 v83, v83, v83
	v_mul_f32_e32 v91, v91, v91
	v_mul_f32_e32 v85, v85, v85
	v_fmac_f32_e32 v89, v88, v88
	v_fmac_f32_e32 v83, v82, v82
	v_fmac_f32_e32 v91, v90, v90
	v_fmac_f32_e32 v85, v84, v84
	v_add_f32_e32 v82, v89, v83
	v_add_f32_e32 v83, v91, v85
	v_add_f32_e32 v88, v82, v83
	global_store_dwordx4 v[86:87], v[72:75], off
	s_waitcnt vmcnt(18)
	v_mov_b32_e32 v76, v196
	v_mov_b32_e32 v77, v197
	v_mov_b32_e32 v78, v198
	v_mov_b32_e32 v79, v199
	v_lshlrev_b32_e32 v82, 16, v76
	v_and_b32_e32 v83, 0xffff0000, v76
	v_lshlrev_b32_e32 v76, 16, v77
	v_and_b32_e32 v77, 0xffff0000, v77
	v_lshlrev_b32_e32 v84, 16, v78
	v_and_b32_e32 v85, 0xffff0000, v78
	v_lshlrev_b32_e32 v78, 16, v79
	v_and_b32_e32 v79, 0xffff0000, v79
	v_pk_add_f32 v[70:71], v[70:71], v[76:77]
	v_pk_add_f32 v[68:69], v[68:69], v[82:83]
	v_pk_add_f32 v[76:77], v[66:67], v[78:79]
	v_pk_add_f32 v[78:79], v[64:65], v[84:85]
	v_mul_f32_e32 v64, v69, v69
	v_mul_f32_e32 v65, v71, v71
	v_mul_f32_e32 v66, v79, v79
	v_mul_f32_e32 v67, v77, v77
	v_fmac_f32_e32 v64, v68, v68
	v_fmac_f32_e32 v65, v70, v70
	v_fmac_f32_e32 v66, v78, v78
	v_fmac_f32_e32 v67, v76, v76
	v_add_f32_e32 v64, v64, v65
	v_add_f32_e32 v65, v66, v67
	v_add_f32_e32 v64, v64, v65
	v_add_f32_e32 v64, v88, v64
	v_mov_b32_e32 v65, v64
	s_nop 1
	v_permlane16_swap_b32_e32 v64, v65
	v_cvt_pk_bf16_f32 v66, v68, v69
	v_cvt_pk_bf16_f32 v67, v70, v71
	v_cvt_pk_bf16_f32 v68, v78, v79
	v_cvt_pk_bf16_f32 v69, v76, v77
	s_waitcnt lgkmcnt(0)
	v_add_f32_e32 v64, v64, v65
	v_mov_b32_e32 v65, v64
	s_nop 1
	v_permlane32_swap_b32_e32 v64, v65
	global_store_dwordx4 v[86:87], v[66:69], off offset:256
	s_and_saveexec_b64 s[46:47], vcc
	s_cbranch_execz .LBB0_744
	s_waitcnt lgkmcnt(0)
	v_add_f32_e32 v66, v64, v65
	s_lshl_b32 s26, s12, 2
	v_lshlrev_b64 v[64:65], 6, v[80:81]
	s_ashr_i32 s27, s26, 31
	v_lshl_add_u64 v[64:65], s[10:11], 0, v[64:65]
	v_lshl_add_u64 v[64:65], s[26:27], 2, v[64:65]
	s_lshl_b32 s14, s60, 2
	v_lshl_add_u64 v[64:65], v[64:65], 0, s[14:15]
	global_store_dword v[64:65], v66, off
.LBB0_744:
	s_or_b64 exec, exec, s[46:47]
	v_add_u32_e32 v64, 0x80, v146
	s_waitcnt lgkmcnt(0)
	v_ashrrev_i32_e32 v65, 31, v64
	v_lshlrev_b64 v[66:67], 11, v[64:65]
	v_lshl_add_u64 v[66:67], s[18:19], 0, v[66:67]
	v_lshl_add_u64 v[70:71], v[144:145], 1, v[66:67]
	s_waitcnt vmcnt(19)
	v_mov_b32_e32 v66, v200
	v_mov_b32_e32 v67, v201
	v_mov_b32_e32 v68, v202
	v_mov_b32_e32 v69, v203
	v_lshlrev_b32_e32 v72, 16, v66
	v_and_b32_e32 v73, 0xffff0000, v66
	v_lshlrev_b32_e32 v66, 16, v67
	v_and_b32_e32 v67, 0xffff0000, v67
	v_lshlrev_b32_e32 v74, 16, v68
	v_and_b32_e32 v75, 0xffff0000, v68
	v_lshlrev_b32_e32 v68, 16, v69
	v_and_b32_e32 v69, 0xffff0000, v69
	v_pk_add_f32 v[66:67], v[62:63], v[66:67]
	v_pk_add_f32 v[72:73], v[60:61], v[72:73]
	v_pk_add_f32 v[68:69], v[58:59], v[68:69]
	v_pk_add_f32 v[74:75], v[56:57], v[74:75]
	v_cvt_pk_bf16_f32 v56, v72, v73
	v_cvt_pk_bf16_f32 v57, v66, v67
	v_mul_f32_e32 v73, v73, v73
	v_cvt_pk_bf16_f32 v58, v74, v75
	v_cvt_pk_bf16_f32 v59, v68, v69
	v_mul_f32_e32 v67, v67, v67
	v_mul_f32_e32 v75, v75, v75
	v_mul_f32_e32 v69, v69, v69
	v_fmac_f32_e32 v73, v72, v72
	v_fmac_f32_e32 v67, v66, v66
	v_fmac_f32_e32 v75, v74, v74
	v_fmac_f32_e32 v69, v68, v68
	v_add_f32_e32 v66, v73, v67
	v_add_f32_e32 v67, v75, v69
	v_add_f32_e32 v72, v66, v67
	global_store_dwordx4 v[70:71], v[56:59], off
	s_waitcnt vmcnt(19)
	v_mov_b32_e32 v60, v204
	v_mov_b32_e32 v61, v205
	v_mov_b32_e32 v62, v206
	v_mov_b32_e32 v63, v207
	v_lshlrev_b32_e32 v66, 16, v60
	v_and_b32_e32 v67, 0xffff0000, v60
	v_lshlrev_b32_e32 v60, 16, v61
	v_and_b32_e32 v61, 0xffff0000, v61
	v_lshlrev_b32_e32 v68, 16, v62
	v_and_b32_e32 v69, 0xffff0000, v62
	v_lshlrev_b32_e32 v62, 16, v63
	v_and_b32_e32 v63, 0xffff0000, v63
	v_pk_add_f32 v[54:55], v[54:55], v[60:61]
	v_pk_add_f32 v[52:53], v[52:53], v[66:67]
	v_pk_add_f32 v[60:61], v[50:51], v[62:63]
	v_pk_add_f32 v[62:63], v[48:49], v[68:69]
	v_mul_f32_e32 v48, v53, v53
	v_mul_f32_e32 v49, v55, v55
	v_mul_f32_e32 v50, v63, v63
	v_mul_f32_e32 v51, v61, v61
	v_fmac_f32_e32 v48, v52, v52
	v_fmac_f32_e32 v49, v54, v54
	v_fmac_f32_e32 v50, v62, v62
	v_fmac_f32_e32 v51, v60, v60
	v_add_f32_e32 v48, v48, v49
	v_add_f32_e32 v49, v50, v51
	v_add_f32_e32 v48, v48, v49
	v_add_f32_e32 v48, v72, v48
	v_mov_b32_e32 v49, v48
	s_nop 1
	v_permlane16_swap_b32_e32 v48, v49
	v_cvt_pk_bf16_f32 v50, v52, v53
	v_cvt_pk_bf16_f32 v51, v54, v55
	v_cvt_pk_bf16_f32 v52, v62, v63
	v_cvt_pk_bf16_f32 v53, v60, v61
	s_waitcnt lgkmcnt(0)
	v_add_f32_e32 v48, v48, v49
	v_mov_b32_e32 v49, v48
	s_nop 1
	v_permlane32_swap_b32_e32 v48, v49
	global_store_dwordx4 v[70:71], v[50:53], off offset:256
	s_and_saveexec_b64 s[46:47], vcc
	s_cbranch_execz .LBB0_746
	s_waitcnt lgkmcnt(0)
	v_add_f32_e32 v50, v48, v49
	s_lshl_b32 s26, s12, 2
	v_lshlrev_b64 v[48:49], 6, v[64:65]
	s_ashr_i32 s27, s26, 31
	v_lshl_add_u64 v[48:49], s[10:11], 0, v[48:49]
	v_lshl_add_u64 v[48:49], s[26:27], 2, v[48:49]
	s_lshl_b32 s14, s60, 2
	v_lshl_add_u64 v[48:49], v[48:49], 0, s[14:15]
	global_store_dword v[48:49], v50, off
.LBB0_746:
	s_or_b64 exec, exec, s[46:47]
	v_add_u32_e32 v48, 0x90, v146
	s_waitcnt lgkmcnt(0)
	v_ashrrev_i32_e32 v49, 31, v48
	v_lshlrev_b64 v[50:51], 11, v[48:49]
	v_lshl_add_u64 v[50:51], s[18:19], 0, v[50:51]
	v_lshl_add_u64 v[54:55], v[144:145], 1, v[50:51]
	s_waitcnt vmcnt(20)
	v_mov_b32_e32 v50, v208
	v_mov_b32_e32 v51, v209
	v_mov_b32_e32 v52, v210
	v_mov_b32_e32 v53, v211
	v_lshlrev_b32_e32 v56, 16, v50
	v_and_b32_e32 v57, 0xffff0000, v50
	v_lshlrev_b32_e32 v50, 16, v51
	v_and_b32_e32 v51, 0xffff0000, v51
	v_lshlrev_b32_e32 v58, 16, v52
	v_and_b32_e32 v59, 0xffff0000, v52
	v_lshlrev_b32_e32 v52, 16, v53
	v_and_b32_e32 v53, 0xffff0000, v53
	v_pk_add_f32 v[50:51], v[46:47], v[50:51]
	v_pk_add_f32 v[56:57], v[44:45], v[56:57]
	v_pk_add_f32 v[52:53], v[42:43], v[52:53]
	v_pk_add_f32 v[58:59], v[40:41], v[58:59]
	v_cvt_pk_bf16_f32 v40, v56, v57
	v_cvt_pk_bf16_f32 v41, v50, v51
	v_mul_f32_e32 v57, v57, v57
	v_cvt_pk_bf16_f32 v42, v58, v59
	v_cvt_pk_bf16_f32 v43, v52, v53
	v_mul_f32_e32 v51, v51, v51
	v_mul_f32_e32 v59, v59, v59
	v_mul_f32_e32 v53, v53, v53
	v_fmac_f32_e32 v57, v56, v56
	v_fmac_f32_e32 v51, v50, v50
	v_fmac_f32_e32 v59, v58, v58
	v_fmac_f32_e32 v53, v52, v52
	v_add_f32_e32 v50, v57, v51
	v_add_f32_e32 v51, v59, v53
	v_add_f32_e32 v56, v50, v51
	global_store_dwordx4 v[54:55], v[40:43], off
	s_waitcnt vmcnt(20)
	v_mov_b32_e32 v44, v212
	v_mov_b32_e32 v45, v213
	v_mov_b32_e32 v46, v214
	v_mov_b32_e32 v47, v215
	v_lshlrev_b32_e32 v50, 16, v44
	v_and_b32_e32 v51, 0xffff0000, v44
	v_lshlrev_b32_e32 v44, 16, v45
	v_and_b32_e32 v45, 0xffff0000, v45
	v_lshlrev_b32_e32 v52, 16, v46
	v_and_b32_e32 v53, 0xffff0000, v46
	v_lshlrev_b32_e32 v46, 16, v47
	v_and_b32_e32 v47, 0xffff0000, v47
	v_pk_add_f32 v[38:39], v[38:39], v[44:45]
	v_pk_add_f32 v[36:37], v[36:37], v[50:51]
	v_pk_add_f32 v[44:45], v[34:35], v[46:47]
	v_pk_add_f32 v[46:47], v[32:33], v[52:53]
	v_mul_f32_e32 v32, v37, v37
	v_mul_f32_e32 v33, v39, v39
	v_mul_f32_e32 v34, v47, v47
	v_mul_f32_e32 v35, v45, v45
	v_fmac_f32_e32 v32, v36, v36
	v_fmac_f32_e32 v33, v38, v38
	v_fmac_f32_e32 v34, v46, v46
	v_fmac_f32_e32 v35, v44, v44
	v_add_f32_e32 v32, v32, v33
	v_add_f32_e32 v33, v34, v35
	v_add_f32_e32 v32, v32, v33
	v_add_f32_e32 v32, v56, v32
	v_mov_b32_e32 v33, v32
	s_nop 1
	v_permlane16_swap_b32_e32 v32, v33
	v_cvt_pk_bf16_f32 v34, v36, v37
	v_cvt_pk_bf16_f32 v35, v38, v39
	v_cvt_pk_bf16_f32 v36, v46, v47
	v_cvt_pk_bf16_f32 v37, v44, v45
	s_waitcnt lgkmcnt(0)
	v_add_f32_e32 v32, v32, v33
	v_mov_b32_e32 v33, v32
	s_nop 1
	v_permlane32_swap_b32_e32 v32, v33
	global_store_dwordx4 v[54:55], v[34:37], off offset:256
	s_and_saveexec_b64 s[46:47], vcc
	s_cbranch_execz .LBB0_748
	s_waitcnt lgkmcnt(0)
	v_add_f32_e32 v34, v32, v33
	s_lshl_b32 s26, s12, 2
	v_lshlrev_b64 v[32:33], 6, v[48:49]
	s_ashr_i32 s27, s26, 31
	v_lshl_add_u64 v[32:33], s[10:11], 0, v[32:33]
	v_lshl_add_u64 v[32:33], s[26:27], 2, v[32:33]
	s_lshl_b32 s14, s60, 2
	v_lshl_add_u64 v[32:33], v[32:33], 0, s[14:15]
	global_store_dword v[32:33], v34, off
.LBB0_748:
	s_or_b64 exec, exec, s[46:47]
	v_add_u32_e32 v32, 0xa0, v146
	s_waitcnt lgkmcnt(0)
	v_ashrrev_i32_e32 v33, 31, v32
	v_lshlrev_b64 v[34:35], 11, v[32:33]
	v_lshl_add_u64 v[34:35], s[18:19], 0, v[34:35]
	v_lshl_add_u64 v[38:39], v[144:145], 1, v[34:35]
	s_waitcnt vmcnt(21)
	v_mov_b32_e32 v34, v216
	v_mov_b32_e32 v35, v217
	v_mov_b32_e32 v36, v218
	v_mov_b32_e32 v37, v219
	v_lshlrev_b32_e32 v40, 16, v34
	v_and_b32_e32 v41, 0xffff0000, v34
	v_lshlrev_b32_e32 v34, 16, v35
	v_and_b32_e32 v35, 0xffff0000, v35
	v_lshlrev_b32_e32 v42, 16, v36
	v_and_b32_e32 v43, 0xffff0000, v36
	v_lshlrev_b32_e32 v36, 16, v37
	v_and_b32_e32 v37, 0xffff0000, v37
	v_pk_add_f32 v[34:35], v[30:31], v[34:35]
	v_pk_add_f32 v[40:41], v[28:29], v[40:41]
	v_pk_add_f32 v[36:37], v[26:27], v[36:37]
	v_pk_add_f32 v[42:43], v[24:25], v[42:43]
	v_cvt_pk_bf16_f32 v24, v40, v41
	v_cvt_pk_bf16_f32 v25, v34, v35
	v_mul_f32_e32 v41, v41, v41
	v_cvt_pk_bf16_f32 v26, v42, v43
	v_cvt_pk_bf16_f32 v27, v36, v37
	v_mul_f32_e32 v35, v35, v35
	v_mul_f32_e32 v43, v43, v43
	v_mul_f32_e32 v37, v37, v37
	v_fmac_f32_e32 v41, v40, v40
	v_fmac_f32_e32 v35, v34, v34
	v_fmac_f32_e32 v43, v42, v42
	v_fmac_f32_e32 v37, v36, v36
	v_add_f32_e32 v34, v41, v35
	v_add_f32_e32 v35, v43, v37
	v_add_f32_e32 v40, v34, v35
	global_store_dwordx4 v[38:39], v[24:27], off
	s_waitcnt vmcnt(21)
	v_mov_b32_e32 v28, v220
	v_mov_b32_e32 v29, v221
	v_mov_b32_e32 v30, v222
	v_mov_b32_e32 v31, v223
	v_lshlrev_b32_e32 v34, 16, v28
	v_and_b32_e32 v35, 0xffff0000, v28
	v_lshlrev_b32_e32 v28, 16, v29
	v_and_b32_e32 v29, 0xffff0000, v29
	v_lshlrev_b32_e32 v36, 16, v30
	v_and_b32_e32 v37, 0xffff0000, v30
	v_lshlrev_b32_e32 v30, 16, v31
	v_and_b32_e32 v31, 0xffff0000, v31
	v_pk_add_f32 v[22:23], v[22:23], v[28:29]
	v_pk_add_f32 v[20:21], v[20:21], v[34:35]
	v_pk_add_f32 v[28:29], v[18:19], v[30:31]
	v_pk_add_f32 v[30:31], v[16:17], v[36:37]
	v_mul_f32_e32 v16, v21, v21
	v_mul_f32_e32 v17, v23, v23
	v_mul_f32_e32 v18, v31, v31
	v_mul_f32_e32 v19, v29, v29
	v_fmac_f32_e32 v16, v20, v20
	v_fmac_f32_e32 v17, v22, v22
	v_fmac_f32_e32 v18, v30, v30
	v_fmac_f32_e32 v19, v28, v28
	v_add_f32_e32 v16, v16, v17
	v_add_f32_e32 v17, v18, v19
	v_add_f32_e32 v16, v16, v17
	v_add_f32_e32 v16, v40, v16
	v_mov_b32_e32 v17, v16
	s_nop 1
	v_permlane16_swap_b32_e32 v16, v17
	v_cvt_pk_bf16_f32 v18, v20, v21
	v_cvt_pk_bf16_f32 v19, v22, v23
	v_cvt_pk_bf16_f32 v20, v30, v31
	v_cvt_pk_bf16_f32 v21, v28, v29
	s_waitcnt lgkmcnt(0)
	v_add_f32_e32 v16, v16, v17
	v_mov_b32_e32 v17, v16
	s_nop 1
	v_permlane32_swap_b32_e32 v16, v17
	global_store_dwordx4 v[38:39], v[18:21], off offset:256
	s_and_saveexec_b64 s[46:47], vcc
	s_cbranch_execz .LBB0_750
	s_waitcnt lgkmcnt(0)
	v_add_f32_e32 v18, v16, v17
	s_lshl_b32 s26, s12, 2
	v_lshlrev_b64 v[16:17], 6, v[32:33]
	s_ashr_i32 s27, s26, 31
	v_lshl_add_u64 v[16:17], s[10:11], 0, v[16:17]
	v_lshl_add_u64 v[16:17], s[26:27], 2, v[16:17]
	s_lshl_b32 s14, s60, 2
	v_lshl_add_u64 v[16:17], v[16:17], 0, s[14:15]
	global_store_dword v[16:17], v18, off
.LBB0_750:
	s_or_b64 exec, exec, s[46:47]
	v_add_u32_e32 v16, 0xb0, v146
	s_waitcnt lgkmcnt(0)
	v_ashrrev_i32_e32 v17, 31, v16
	v_lshlrev_b64 v[18:19], 11, v[16:17]
	v_lshl_add_u64 v[18:19], s[18:19], 0, v[18:19]
	v_lshl_add_u64 v[22:23], v[144:145], 1, v[18:19]
	s_waitcnt vmcnt(22)
	v_mov_b32_e32 v18, v226
	v_mov_b32_e32 v19, v227
	v_mov_b32_e32 v20, v228
	v_mov_b32_e32 v21, v229
	v_lshlrev_b32_e32 v24, 16, v18
	v_and_b32_e32 v25, 0xffff0000, v18
	v_lshlrev_b32_e32 v18, 16, v19
	v_and_b32_e32 v19, 0xffff0000, v19
	v_lshlrev_b32_e32 v26, 16, v20
	v_and_b32_e32 v27, 0xffff0000, v20
	v_lshlrev_b32_e32 v20, 16, v21
	v_and_b32_e32 v21, 0xffff0000, v21
	v_pk_add_f32 v[18:19], v[14:15], v[18:19]
	v_pk_add_f32 v[24:25], v[12:13], v[24:25]
	v_pk_add_f32 v[20:21], v[10:11], v[20:21]
	v_pk_add_f32 v[26:27], v[8:9], v[26:27]
	v_cvt_pk_bf16_f32 v8, v24, v25
	v_cvt_pk_bf16_f32 v9, v18, v19
	v_mul_f32_e32 v25, v25, v25
	v_cvt_pk_bf16_f32 v10, v26, v27
	v_cvt_pk_bf16_f32 v11, v20, v21
	v_mul_f32_e32 v19, v19, v19
	v_mul_f32_e32 v27, v27, v27
	v_mul_f32_e32 v21, v21, v21
	v_fmac_f32_e32 v25, v24, v24
	v_fmac_f32_e32 v19, v18, v18
	v_fmac_f32_e32 v27, v26, v26
	v_fmac_f32_e32 v21, v20, v20
	v_add_f32_e32 v18, v25, v19
	v_add_f32_e32 v19, v27, v21
	v_add_f32_e32 v24, v18, v19
	global_store_dwordx4 v[22:23], v[8:11], off
	s_waitcnt vmcnt(22)
	v_mov_b32_e32 v12, v230
	v_mov_b32_e32 v13, v231
	v_mov_b32_e32 v14, v232
	v_mov_b32_e32 v15, v233
	v_lshlrev_b32_e32 v18, 16, v12
	v_and_b32_e32 v19, 0xffff0000, v12
	v_lshlrev_b32_e32 v12, 16, v13
	v_and_b32_e32 v13, 0xffff0000, v13
	v_lshlrev_b32_e32 v20, 16, v14
	v_and_b32_e32 v21, 0xffff0000, v14
	v_lshlrev_b32_e32 v14, 16, v15
	v_and_b32_e32 v15, 0xffff0000, v15
	v_pk_add_f32 v[6:7], v[6:7], v[12:13]
	v_pk_add_f32 v[4:5], v[4:5], v[18:19]
	v_pk_add_f32 v[12:13], v[2:3], v[14:15]
	v_pk_add_f32 v[14:15], v[0:1], v[20:21]
	v_mul_f32_e32 v0, v5, v5
	v_mul_f32_e32 v1, v7, v7
	v_mul_f32_e32 v2, v15, v15
	v_mul_f32_e32 v3, v13, v13
	v_fmac_f32_e32 v0, v4, v4
	v_fmac_f32_e32 v1, v6, v6
	v_fmac_f32_e32 v2, v14, v14
	v_fmac_f32_e32 v3, v12, v12
	v_add_f32_e32 v0, v0, v1
	v_add_f32_e32 v1, v2, v3
	v_add_f32_e32 v0, v0, v1
	v_add_f32_e32 v0, v24, v0
	v_mov_b32_e32 v1, v0
	s_nop 1
	v_permlane16_swap_b32_e32 v0, v1
	v_cvt_pk_bf16_f32 v2, v4, v5
	v_cvt_pk_bf16_f32 v3, v6, v7
	v_cvt_pk_bf16_f32 v4, v14, v15
	v_cvt_pk_bf16_f32 v5, v12, v13
	s_waitcnt lgkmcnt(0)
	v_add_f32_e32 v0, v0, v1
	v_mov_b32_e32 v1, v0
	s_nop 1
	v_permlane32_swap_b32_e32 v0, v1
	global_store_dwordx4 v[22:23], v[2:5], off offset:256
	s_and_saveexec_b64 s[46:47], vcc
	s_cbranch_execz .LBB0_752
	s_waitcnt lgkmcnt(0)
	v_add_f32_e32 v2, v0, v1
	s_lshl_b32 s26, s12, 2
	v_lshlrev_b64 v[0:1], 6, v[16:17]
	s_ashr_i32 s27, s26, 31
	v_lshl_add_u64 v[0:1], s[10:11], 0, v[0:1]
	v_lshl_add_u64 v[0:1], s[26:27], 2, v[0:1]
	s_lshl_b32 s14, s60, 2
	v_lshl_add_u64 v[0:1], v[0:1], 0, s[14:15]
	global_store_dword v[0:1], v2, off

.LBB0_1062:
	s_lshl_b32 s16, s16, 8
	v_mov_b32_e32 v166, v149
	v_mov_b32_e32 v167, v148
	s_add_i32 s16, s16, s63
	s_lshl_b32 s22, s56, 8
	v_add_u32_e32 v146, s16, v166
	s_or_b32 s22, s22, s64
	v_ashrrev_i32_e32 v147, 31, v146
	v_lshl_add_u32 v144, v167, 3, s22
	v_lshlrev_b64 v[154:155], 11, v[146:147]
	v_ashrrev_i32_e32 v145, 31, v144
	v_lshl_add_u64 v[154:155], s[36:37], 0, v[154:155]
	v_lshl_add_u64 v[158:159], v[144:145], 1, v[154:155]
	v_mov_b32_e32 v236, 0x8000
	v_mov_b32_e32 v237, 0
	v_mov_b32_e32 v238, 0x28000
	v_mov_b32_e32 v239, 0
	global_load_dwordx4 v[168:171], v[158:159], off
	global_load_dwordx4 v[172:175], v[158:159], off offset:256
	v_lshl_add_u64 v[234:235], v[158:159], 0, v[236:237]
	global_load_dwordx4 v[176:179], v[234:235], off
	global_load_dwordx4 v[180:183], v[234:235], off offset:256
	v_lshl_add_u64 v[234:235], v[234:235], 0, v[236:237]
	global_load_dwordx4 v[184:187], v[234:235], off
	global_load_dwordx4 v[188:191], v[234:235], off offset:256
	v_lshl_add_u64 v[234:235], v[234:235], 0, v[236:237]
	global_load_dwordx4 v[192:195], v[234:235], off
	global_load_dwordx4 v[196:199], v[234:235], off offset:256
	v_lshl_add_u64 v[234:235], v[234:235], 0, v[238:239]
	global_load_dwordx4 v[200:203], v[234:235], off
	global_load_dwordx4 v[204:207], v[234:235], off offset:256
	v_lshl_add_u64 v[234:235], v[234:235], 0, v[236:237]
	global_load_dwordx4 v[208:211], v[234:235], off
	global_load_dwordx4 v[212:215], v[234:235], off offset:256
	v_lshl_add_u64 v[234:235], v[234:235], 0, v[236:237]
	global_load_dwordx4 v[216:219], v[234:235], off
	global_load_dwordx4 v[220:223], v[234:235], off offset:256
	v_lshl_add_u64 v[234:235], v[234:235], 0, v[236:237]
	global_load_dwordx4 v[226:229], v[234:235], off
	global_load_dwordx4 v[230:233], v[234:235], off offset:256
	v_cmp_eq_u32_e32 vcc, 0, v167
	s_waitcnt vmcnt(15)
	v_mov_b32_e32 v154, v168
	v_mov_b32_e32 v155, v169
	v_mov_b32_e32 v156, v170
	v_mov_b32_e32 v157, v171
	v_lshlrev_b32_e32 v160, 16, v154
	v_and_b32_e32 v161, 0xffff0000, v154
	v_lshlrev_b32_e32 v154, 16, v155
	v_and_b32_e32 v155, 0xffff0000, v155
	v_lshlrev_b32_e32 v162, 16, v156
	v_and_b32_e32 v163, 0xffff0000, v156
	v_lshlrev_b32_e32 v156, 16, v157
	v_and_b32_e32 v157, 0xffff0000, v157
	v_pk_add_f32 v[126:127], v[126:127], v[154:155]
	v_pk_add_f32 v[160:161], v[124:125], v[160:161]
	v_pk_add_f32 v[164:165], v[122:123], v[156:157]
	v_pk_add_f32 v[162:163], v[120:121], v[162:163]
	v_cvt_pk_bf16_f32 v122, v160, v161
	v_cvt_pk_bf16_f32 v123, v126, v127
	v_mul_f32_e32 v161, v161, v161
	v_cvt_pk_bf16_f32 v124, v162, v163
	v_cvt_pk_bf16_f32 v125, v164, v165
	v_mul_f32_e32 v127, v127, v127
	v_mul_f32_e32 v163, v163, v163
	v_mul_f32_e32 v165, v165, v165
	v_fmac_f32_e32 v161, v160, v160
	v_fmac_f32_e32 v127, v126, v126
	v_fmac_f32_e32 v163, v162, v162
	v_fmac_f32_e32 v165, v164, v164
	v_add_f32_e32 v126, v161, v127
	v_add_f32_e32 v127, v163, v165
	v_add_f32_e32 v162, v126, v127
	v_lshlrev_b32_e32 v120, 2, v166
	v_lshl_add_u32 v121, v167, 6, v120
	v_xor_b32_e32 v120, 64, v121
	global_store_dwordx4 v[158:159], v[122:125], off
	s_waitcnt vmcnt(15)
	v_mov_b32_e32 v154, v172
	v_mov_b32_e32 v155, v173
	v_mov_b32_e32 v156, v174
	v_mov_b32_e32 v157, v175
	v_lshlrev_b32_e32 v126, 16, v154
	v_and_b32_e32 v127, 0xffff0000, v154
	v_lshlrev_b32_e32 v154, 16, v155
	v_and_b32_e32 v155, 0xffff0000, v155
	v_lshlrev_b32_e32 v160, 16, v156
	v_and_b32_e32 v161, 0xffff0000, v156
	v_lshlrev_b32_e32 v156, 16, v157
	v_and_b32_e32 v157, 0xffff0000, v157
	v_pk_add_f32 v[118:119], v[118:119], v[154:155]
	v_pk_add_f32 v[116:117], v[116:117], v[126:127]
	v_pk_add_f32 v[126:127], v[114:115], v[156:157]
	v_pk_add_f32 v[154:155], v[112:113], v[160:161]
	v_mul_f32_e32 v112, v117, v117
	v_mul_f32_e32 v113, v119, v119
	v_mul_f32_e32 v114, v155, v155
	v_mul_f32_e32 v115, v127, v127
	v_fmac_f32_e32 v112, v116, v116
	v_fmac_f32_e32 v113, v118, v118
	v_fmac_f32_e32 v114, v154, v154
	v_fmac_f32_e32 v115, v126, v126
	v_add_f32_e32 v112, v112, v113
	v_add_f32_e32 v113, v114, v115
	v_add_f32_e32 v112, v112, v113
	v_add_f32_e32 v112, v162, v112
	v_mov_b32_e32 v113, v112
	s_nop 1
	v_permlane16_swap_b32_e32 v112, v113
	v_xor_b32_e32 v114, 0x80, v121
	v_cvt_pk_bf16_f32 v116, v116, v117
	v_cvt_pk_bf16_f32 v117, v118, v119
	v_cvt_pk_bf16_f32 v118, v154, v155
	s_waitcnt lgkmcnt(0)
	v_add_f32_e32 v112, v112, v113
	v_mov_b32_e32 v113, v112
	s_nop 1
	v_permlane32_swap_b32_e32 v112, v113
	v_cvt_pk_bf16_f32 v119, v126, v127
	global_store_dwordx4 v[158:159], v[116:119], off offset:256
	s_and_saveexec_b64 s[44:45], vcc
	s_cbranch_execz .LBB0_1064
	s_waitcnt lgkmcnt(0)
	v_add_f32_e32 v115, v112, v113
	s_lshl_b32 s22, s56, 2
	v_lshlrev_b64 v[112:113], 6, v[146:147]
	s_ashr_i32 s23, s22, 31
	v_lshl_add_u64 v[112:113], s[14:15], 0, v[112:113]
	v_lshl_add_u64 v[112:113], s[22:23], 2, v[112:113]
	s_lshl_b32 s16, s62, 2
	v_lshl_add_u64 v[112:113], v[112:113], 0, s[16:17]
	global_store_dword v[112:113], v115, off
.LBB0_1064:
	s_or_b64 exec, exec, s[44:45]
	v_add_u32_e32 v112, 16, v146
	s_waitcnt lgkmcnt(0)
	v_ashrrev_i32_e32 v113, 31, v112
	v_lshlrev_b64 v[116:117], 11, v[112:113]
	v_lshl_add_u64 v[116:117], s[36:37], 0, v[116:117]
	v_lshl_add_u64 v[122:123], v[144:145], 1, v[116:117]
	s_waitcnt vmcnt(16)
	v_mov_b32_e32 v116, v176
	v_mov_b32_e32 v117, v177
	v_mov_b32_e32 v118, v178
	v_mov_b32_e32 v119, v179
	v_lshlrev_b32_e32 v124, 16, v116
	v_and_b32_e32 v125, 0xffff0000, v116
	v_lshlrev_b32_e32 v116, 16, v117
	v_and_b32_e32 v117, 0xffff0000, v117
	v_lshlrev_b32_e32 v126, 16, v118
	v_and_b32_e32 v127, 0xffff0000, v118
	v_lshlrev_b32_e32 v118, 16, v119
	v_and_b32_e32 v119, 0xffff0000, v119
	v_pk_add_f32 v[116:117], v[110:111], v[116:117]
	v_pk_add_f32 v[124:125], v[108:109], v[124:125]
	v_pk_add_f32 v[118:119], v[106:107], v[118:119]
	v_pk_add_f32 v[126:127], v[104:105], v[126:127]
	v_cvt_pk_bf16_f32 v104, v124, v125
	v_cvt_pk_bf16_f32 v105, v116, v117
	v_mul_f32_e32 v115, v125, v125
	v_cvt_pk_bf16_f32 v106, v126, v127
	v_cvt_pk_bf16_f32 v107, v118, v119
	v_mul_f32_e32 v117, v117, v117
	v_mul_f32_e32 v121, v127, v127
	v_mul_f32_e32 v119, v119, v119
	v_fmac_f32_e32 v115, v124, v124
	v_fmac_f32_e32 v117, v116, v116
	v_fmac_f32_e32 v121, v126, v126
	v_fmac_f32_e32 v119, v118, v118
	v_add_f32_e32 v115, v115, v117
	v_add_f32_e32 v116, v121, v119
	v_add_f32_e32 v115, v115, v116
	global_store_dwordx4 v[122:123], v[104:107], off
	s_waitcnt vmcnt(16)
	v_mov_b32_e32 v108, v180
	v_mov_b32_e32 v109, v181
	v_mov_b32_e32 v110, v182
	v_mov_b32_e32 v111, v183
	v_lshlrev_b32_e32 v116, 16, v108
	v_and_b32_e32 v117, 0xffff0000, v108
	v_lshlrev_b32_e32 v108, 16, v109
	v_and_b32_e32 v109, 0xffff0000, v109
	v_lshlrev_b32_e32 v118, 16, v110
	v_and_b32_e32 v119, 0xffff0000, v110
	v_lshlrev_b32_e32 v110, 16, v111
	v_and_b32_e32 v111, 0xffff0000, v111
	v_pk_add_f32 v[102:103], v[102:103], v[108:109]
	v_pk_add_f32 v[100:101], v[100:101], v[116:117]
	v_pk_add_f32 v[108:109], v[98:99], v[110:111]
	v_pk_add_f32 v[110:111], v[96:97], v[118:119]
	v_mul_f32_e32 v96, v101, v101
	v_mul_f32_e32 v97, v103, v103
	v_mul_f32_e32 v98, v111, v111
	v_mul_f32_e32 v99, v109, v109
	v_fmac_f32_e32 v96, v100, v100
	v_fmac_f32_e32 v97, v102, v102
	v_fmac_f32_e32 v98, v110, v110
	v_fmac_f32_e32 v99, v108, v108
	v_add_f32_e32 v96, v96, v97
	v_add_f32_e32 v97, v98, v99
	v_add_f32_e32 v96, v96, v97
	v_add_f32_e32 v96, v115, v96
	v_mov_b32_e32 v97, v96
	s_nop 1
	v_permlane16_swap_b32_e32 v96, v97
	v_cvt_pk_bf16_f32 v98, v100, v101
	v_cvt_pk_bf16_f32 v99, v102, v103
	v_cvt_pk_bf16_f32 v100, v110, v111
	v_cvt_pk_bf16_f32 v101, v108, v109
	s_waitcnt lgkmcnt(0)
	v_add_f32_e32 v96, v96, v97
	v_mov_b32_e32 v97, v96
	s_nop 1
	v_permlane32_swap_b32_e32 v96, v97
	global_store_dwordx4 v[122:123], v[98:101], off offset:256
	s_and_saveexec_b64 s[44:45], vcc
	s_cbranch_execz .LBB0_1066
	s_waitcnt lgkmcnt(0)
	v_add_f32_e32 v98, v96, v97
	s_lshl_b32 s22, s56, 2
	v_lshlrev_b64 v[96:97], 6, v[112:113]
	s_ashr_i32 s23, s22, 31
	v_lshl_add_u64 v[96:97], s[14:15], 0, v[96:97]
	v_lshl_add_u64 v[96:97], s[22:23], 2, v[96:97]
	s_lshl_b32 s16, s62, 2
	v_lshl_add_u64 v[96:97], v[96:97], 0, s[16:17]
	global_store_dword v[96:97], v98, off
.LBB0_1066:
	s_or_b64 exec, exec, s[44:45]
	v_add_u32_e32 v96, 32, v146
	s_waitcnt lgkmcnt(0)
	v_ashrrev_i32_e32 v97, 31, v96
	v_lshlrev_b64 v[98:99], 11, v[96:97]
	v_lshl_add_u64 v[98:99], s[36:37], 0, v[98:99]
	v_lshl_add_u64 v[102:103], v[144:145], 1, v[98:99]
	s_waitcnt vmcnt(17)
	v_mov_b32_e32 v98, v184
	v_mov_b32_e32 v99, v185
	v_mov_b32_e32 v100, v186
	v_mov_b32_e32 v101, v187
	v_lshlrev_b32_e32 v104, 16, v98
	v_and_b32_e32 v105, 0xffff0000, v98
	v_lshlrev_b32_e32 v98, 16, v99
	v_and_b32_e32 v99, 0xffff0000, v99
	v_lshlrev_b32_e32 v106, 16, v100
	v_and_b32_e32 v107, 0xffff0000, v100
	v_lshlrev_b32_e32 v100, 16, v101
	v_and_b32_e32 v101, 0xffff0000, v101
	v_pk_add_f32 v[98:99], v[94:95], v[98:99]
	v_pk_add_f32 v[104:105], v[92:93], v[104:105]
	v_pk_add_f32 v[100:101], v[90:91], v[100:101]
	v_pk_add_f32 v[106:107], v[88:89], v[106:107]
	v_cvt_pk_bf16_f32 v88, v104, v105
	v_cvt_pk_bf16_f32 v89, v98, v99
	v_mul_f32_e32 v105, v105, v105
	v_cvt_pk_bf16_f32 v90, v106, v107
	v_cvt_pk_bf16_f32 v91, v100, v101
	v_mul_f32_e32 v99, v99, v99
	v_mul_f32_e32 v107, v107, v107
	v_mul_f32_e32 v101, v101, v101
	v_fmac_f32_e32 v105, v104, v104
	v_fmac_f32_e32 v99, v98, v98
	v_fmac_f32_e32 v107, v106, v106
	v_fmac_f32_e32 v101, v100, v100
	v_add_f32_e32 v98, v105, v99
	v_add_f32_e32 v99, v107, v101
	v_add_f32_e32 v104, v98, v99
	global_store_dwordx4 v[102:103], v[88:91], off
	s_waitcnt vmcnt(17)
	v_mov_b32_e32 v92, v188
	v_mov_b32_e32 v93, v189
	v_mov_b32_e32 v94, v190
	v_mov_b32_e32 v95, v191
	v_lshlrev_b32_e32 v98, 16, v92
	v_and_b32_e32 v99, 0xffff0000, v92
	v_lshlrev_b32_e32 v92, 16, v93
	v_and_b32_e32 v93, 0xffff0000, v93
	v_lshlrev_b32_e32 v100, 16, v94
	v_and_b32_e32 v101, 0xffff0000, v94
	v_lshlrev_b32_e32 v94, 16, v95
	v_and_b32_e32 v95, 0xffff0000, v95
	v_pk_add_f32 v[86:87], v[86:87], v[92:93]
	v_pk_add_f32 v[84:85], v[84:85], v[98:99]
	v_pk_add_f32 v[92:93], v[82:83], v[94:95]
	v_pk_add_f32 v[94:95], v[80:81], v[100:101]
	v_mul_f32_e32 v80, v85, v85
	v_mul_f32_e32 v81, v87, v87
	v_mul_f32_e32 v82, v95, v95
	v_mul_f32_e32 v83, v93, v93
	v_fmac_f32_e32 v80, v84, v84
	v_fmac_f32_e32 v81, v86, v86
	v_fmac_f32_e32 v82, v94, v94
	v_fmac_f32_e32 v83, v92, v92
	v_add_f32_e32 v80, v80, v81
	v_add_f32_e32 v81, v82, v83
	v_add_f32_e32 v80, v80, v81
	v_add_f32_e32 v80, v104, v80
	v_mov_b32_e32 v81, v80
	s_nop 1
	v_permlane16_swap_b32_e32 v80, v81
	v_cvt_pk_bf16_f32 v82, v84, v85
	v_cvt_pk_bf16_f32 v83, v86, v87
	v_cvt_pk_bf16_f32 v84, v94, v95
	v_cvt_pk_bf16_f32 v85, v92, v93
	s_waitcnt lgkmcnt(0)
	v_add_f32_e32 v80, v80, v81
	v_mov_b32_e32 v81, v80
	s_nop 1
	v_permlane32_swap_b32_e32 v80, v81
	global_store_dwordx4 v[102:103], v[82:85], off offset:256
	s_and_saveexec_b64 s[44:45], vcc
	s_cbranch_execz .LBB0_1068
	s_waitcnt lgkmcnt(0)
	v_add_f32_e32 v82, v80, v81
	s_lshl_b32 s22, s56, 2
	v_lshlrev_b64 v[80:81], 6, v[96:97]
	s_ashr_i32 s23, s22, 31
	v_lshl_add_u64 v[80:81], s[14:15], 0, v[80:81]
	v_lshl_add_u64 v[80:81], s[22:23], 2, v[80:81]
	s_lshl_b32 s16, s62, 2
	v_lshl_add_u64 v[80:81], v[80:81], 0, s[16:17]
	global_store_dword v[80:81], v82, off
.LBB0_1068:
	s_or_b64 exec, exec, s[44:45]
	v_add_u32_e32 v80, 48, v146
	s_waitcnt lgkmcnt(0)
	v_ashrrev_i32_e32 v81, 31, v80
	v_lshlrev_b64 v[82:83], 11, v[80:81]
	v_lshl_add_u64 v[82:83], s[36:37], 0, v[82:83]
	v_lshl_add_u64 v[86:87], v[144:145], 1, v[82:83]
	s_waitcnt vmcnt(18)
	v_mov_b32_e32 v82, v192
	v_mov_b32_e32 v83, v193
	v_mov_b32_e32 v84, v194
	v_mov_b32_e32 v85, v195
	v_lshlrev_b32_e32 v88, 16, v82
	v_and_b32_e32 v89, 0xffff0000, v82
	v_lshlrev_b32_e32 v82, 16, v83
	v_and_b32_e32 v83, 0xffff0000, v83
	v_lshlrev_b32_e32 v90, 16, v84
	v_and_b32_e32 v91, 0xffff0000, v84
	v_lshlrev_b32_e32 v84, 16, v85
	v_and_b32_e32 v85, 0xffff0000, v85
	v_pk_add_f32 v[82:83], v[78:79], v[82:83]
	v_pk_add_f32 v[88:89], v[76:77], v[88:89]
	v_pk_add_f32 v[84:85], v[74:75], v[84:85]
	v_pk_add_f32 v[90:91], v[72:73], v[90:91]
	v_cvt_pk_bf16_f32 v72, v88, v89
	v_cvt_pk_bf16_f32 v73, v82, v83
	v_mul_f32_e32 v89, v89, v89
	v_cvt_pk_bf16_f32 v74, v90, v91
	v_cvt_pk_bf16_f32 v75, v84, v85
	v_mul_f32_e32 v83, v83, v83
	v_mul_f32_e32 v91, v91, v91
	v_mul_f32_e32 v85, v85, v85
	v_fmac_f32_e32 v89, v88, v88
	v_fmac_f32_e32 v83, v82, v82
	v_fmac_f32_e32 v91, v90, v90
	v_fmac_f32_e32 v85, v84, v84
	v_add_f32_e32 v82, v89, v83
	v_add_f32_e32 v83, v91, v85
	v_add_f32_e32 v88, v82, v83
	global_store_dwordx4 v[86:87], v[72:75], off
	s_waitcnt vmcnt(18)
	v_mov_b32_e32 v76, v196
	v_mov_b32_e32 v77, v197
	v_mov_b32_e32 v78, v198
	v_mov_b32_e32 v79, v199
	v_lshlrev_b32_e32 v82, 16, v76
	v_and_b32_e32 v83, 0xffff0000, v76
	v_lshlrev_b32_e32 v76, 16, v77
	v_and_b32_e32 v77, 0xffff0000, v77
	v_lshlrev_b32_e32 v84, 16, v78
	v_and_b32_e32 v85, 0xffff0000, v78
	v_lshlrev_b32_e32 v78, 16, v79
	v_and_b32_e32 v79, 0xffff0000, v79
	v_pk_add_f32 v[70:71], v[70:71], v[76:77]
	v_pk_add_f32 v[68:69], v[68:69], v[82:83]
	v_pk_add_f32 v[76:77], v[66:67], v[78:79]
	v_pk_add_f32 v[78:79], v[64:65], v[84:85]
	v_mul_f32_e32 v64, v69, v69
	v_mul_f32_e32 v65, v71, v71
	v_mul_f32_e32 v66, v79, v79
	v_mul_f32_e32 v67, v77, v77
	v_fmac_f32_e32 v64, v68, v68
	v_fmac_f32_e32 v65, v70, v70
	v_fmac_f32_e32 v66, v78, v78
	v_fmac_f32_e32 v67, v76, v76
	v_add_f32_e32 v64, v64, v65
	v_add_f32_e32 v65, v66, v67
	v_add_f32_e32 v64, v64, v65
	v_add_f32_e32 v64, v88, v64
	v_mov_b32_e32 v65, v64
	s_nop 1
	v_permlane16_swap_b32_e32 v64, v65
	v_cvt_pk_bf16_f32 v66, v68, v69
	v_cvt_pk_bf16_f32 v67, v70, v71
	v_cvt_pk_bf16_f32 v68, v78, v79
	v_cvt_pk_bf16_f32 v69, v76, v77
	s_waitcnt lgkmcnt(0)
	v_add_f32_e32 v64, v64, v65
	v_mov_b32_e32 v65, v64
	s_nop 1
	v_permlane32_swap_b32_e32 v64, v65
	global_store_dwordx4 v[86:87], v[66:69], off offset:256
	s_and_saveexec_b64 s[44:45], vcc
	s_cbranch_execz .LBB0_1070
	s_waitcnt lgkmcnt(0)
	v_add_f32_e32 v66, v64, v65
	s_lshl_b32 s22, s56, 2
	v_lshlrev_b64 v[64:65], 6, v[80:81]
	s_ashr_i32 s23, s22, 31
	v_lshl_add_u64 v[64:65], s[14:15], 0, v[64:65]
	v_lshl_add_u64 v[64:65], s[22:23], 2, v[64:65]
	s_lshl_b32 s16, s62, 2
	v_lshl_add_u64 v[64:65], v[64:65], 0, s[16:17]
	global_store_dword v[64:65], v66, off
.LBB0_1070:
	s_or_b64 exec, exec, s[44:45]
	v_add_u32_e32 v64, 0x80, v146
	s_waitcnt lgkmcnt(0)
	v_ashrrev_i32_e32 v65, 31, v64
	v_lshlrev_b64 v[66:67], 11, v[64:65]
	v_lshl_add_u64 v[66:67], s[36:37], 0, v[66:67]
	v_lshl_add_u64 v[70:71], v[144:145], 1, v[66:67]
	s_waitcnt vmcnt(19)
	v_mov_b32_e32 v66, v200
	v_mov_b32_e32 v67, v201
	v_mov_b32_e32 v68, v202
	v_mov_b32_e32 v69, v203
	v_lshlrev_b32_e32 v72, 16, v66
	v_and_b32_e32 v73, 0xffff0000, v66
	v_lshlrev_b32_e32 v66, 16, v67
	v_and_b32_e32 v67, 0xffff0000, v67
	v_lshlrev_b32_e32 v74, 16, v68
	v_and_b32_e32 v75, 0xffff0000, v68
	v_lshlrev_b32_e32 v68, 16, v69
	v_and_b32_e32 v69, 0xffff0000, v69
	v_pk_add_f32 v[66:67], v[62:63], v[66:67]
	v_pk_add_f32 v[72:73], v[60:61], v[72:73]
	v_pk_add_f32 v[68:69], v[58:59], v[68:69]
	v_pk_add_f32 v[74:75], v[56:57], v[74:75]
	v_cvt_pk_bf16_f32 v56, v72, v73
	v_cvt_pk_bf16_f32 v57, v66, v67
	v_mul_f32_e32 v73, v73, v73
	v_cvt_pk_bf16_f32 v58, v74, v75
	v_cvt_pk_bf16_f32 v59, v68, v69
	v_mul_f32_e32 v67, v67, v67
	v_mul_f32_e32 v75, v75, v75
	v_mul_f32_e32 v69, v69, v69
	v_fmac_f32_e32 v73, v72, v72
	v_fmac_f32_e32 v67, v66, v66
	v_fmac_f32_e32 v75, v74, v74
	v_fmac_f32_e32 v69, v68, v68
	v_add_f32_e32 v66, v73, v67
	v_add_f32_e32 v67, v75, v69
	v_add_f32_e32 v72, v66, v67
	global_store_dwordx4 v[70:71], v[56:59], off
	s_waitcnt vmcnt(19)
	v_mov_b32_e32 v60, v204
	v_mov_b32_e32 v61, v205
	v_mov_b32_e32 v62, v206
	v_mov_b32_e32 v63, v207
	v_lshlrev_b32_e32 v66, 16, v60
	v_and_b32_e32 v67, 0xffff0000, v60
	v_lshlrev_b32_e32 v60, 16, v61
	v_and_b32_e32 v61, 0xffff0000, v61
	v_lshlrev_b32_e32 v68, 16, v62
	v_and_b32_e32 v69, 0xffff0000, v62
	v_lshlrev_b32_e32 v62, 16, v63
	v_and_b32_e32 v63, 0xffff0000, v63
	v_pk_add_f32 v[54:55], v[54:55], v[60:61]
	v_pk_add_f32 v[52:53], v[52:53], v[66:67]
	v_pk_add_f32 v[60:61], v[50:51], v[62:63]
	v_pk_add_f32 v[62:63], v[48:49], v[68:69]
	v_mul_f32_e32 v48, v53, v53
	v_mul_f32_e32 v49, v55, v55
	v_mul_f32_e32 v50, v63, v63
	v_mul_f32_e32 v51, v61, v61
	v_fmac_f32_e32 v48, v52, v52
	v_fmac_f32_e32 v49, v54, v54
	v_fmac_f32_e32 v50, v62, v62
	v_fmac_f32_e32 v51, v60, v60
	v_add_f32_e32 v48, v48, v49
	v_add_f32_e32 v49, v50, v51
	v_add_f32_e32 v48, v48, v49
	v_add_f32_e32 v48, v72, v48
	v_mov_b32_e32 v49, v48
	s_nop 1
	v_permlane16_swap_b32_e32 v48, v49
	v_cvt_pk_bf16_f32 v50, v52, v53
	v_cvt_pk_bf16_f32 v51, v54, v55
	v_cvt_pk_bf16_f32 v52, v62, v63
	v_cvt_pk_bf16_f32 v53, v60, v61
	s_waitcnt lgkmcnt(0)
	v_add_f32_e32 v48, v48, v49
	v_mov_b32_e32 v49, v48
	s_nop 1
	v_permlane32_swap_b32_e32 v48, v49
	global_store_dwordx4 v[70:71], v[50:53], off offset:256
	s_and_saveexec_b64 s[44:45], vcc
	s_cbranch_execz .LBB0_1072
	s_waitcnt lgkmcnt(0)
	v_add_f32_e32 v50, v48, v49
	s_lshl_b32 s22, s56, 2
	v_lshlrev_b64 v[48:49], 6, v[64:65]
	s_ashr_i32 s23, s22, 31
	v_lshl_add_u64 v[48:49], s[14:15], 0, v[48:49]
	v_lshl_add_u64 v[48:49], s[22:23], 2, v[48:49]
	s_lshl_b32 s16, s62, 2
	v_lshl_add_u64 v[48:49], v[48:49], 0, s[16:17]
	global_store_dword v[48:49], v50, off
.LBB0_1072:
	s_or_b64 exec, exec, s[44:45]
	v_add_u32_e32 v48, 0x90, v146
	s_waitcnt lgkmcnt(0)
	v_ashrrev_i32_e32 v49, 31, v48
	v_lshlrev_b64 v[50:51], 11, v[48:49]
	v_lshl_add_u64 v[50:51], s[36:37], 0, v[50:51]
	v_lshl_add_u64 v[54:55], v[144:145], 1, v[50:51]
	s_waitcnt vmcnt(20)
	v_mov_b32_e32 v50, v208
	v_mov_b32_e32 v51, v209
	v_mov_b32_e32 v52, v210
	v_mov_b32_e32 v53, v211
	v_lshlrev_b32_e32 v56, 16, v50
	v_and_b32_e32 v57, 0xffff0000, v50
	v_lshlrev_b32_e32 v50, 16, v51
	v_and_b32_e32 v51, 0xffff0000, v51
	v_lshlrev_b32_e32 v58, 16, v52
	v_and_b32_e32 v59, 0xffff0000, v52
	v_lshlrev_b32_e32 v52, 16, v53
	v_and_b32_e32 v53, 0xffff0000, v53
	v_pk_add_f32 v[50:51], v[46:47], v[50:51]
	v_pk_add_f32 v[56:57], v[44:45], v[56:57]
	v_pk_add_f32 v[52:53], v[42:43], v[52:53]
	v_pk_add_f32 v[58:59], v[40:41], v[58:59]
	v_cvt_pk_bf16_f32 v40, v56, v57
	v_cvt_pk_bf16_f32 v41, v50, v51
	v_mul_f32_e32 v57, v57, v57
	v_cvt_pk_bf16_f32 v42, v58, v59
	v_cvt_pk_bf16_f32 v43, v52, v53
	v_mul_f32_e32 v51, v51, v51
	v_mul_f32_e32 v59, v59, v59
	v_mul_f32_e32 v53, v53, v53
	v_fmac_f32_e32 v57, v56, v56
	v_fmac_f32_e32 v51, v50, v50
	v_fmac_f32_e32 v59, v58, v58
	v_fmac_f32_e32 v53, v52, v52
	v_add_f32_e32 v50, v57, v51
	v_add_f32_e32 v51, v59, v53
	v_add_f32_e32 v56, v50, v51
	global_store_dwordx4 v[54:55], v[40:43], off
	s_waitcnt vmcnt(20)
	v_mov_b32_e32 v44, v212
	v_mov_b32_e32 v45, v213
	v_mov_b32_e32 v46, v214
	v_mov_b32_e32 v47, v215
	v_lshlrev_b32_e32 v50, 16, v44
	v_and_b32_e32 v51, 0xffff0000, v44
	v_lshlrev_b32_e32 v44, 16, v45
	v_and_b32_e32 v45, 0xffff0000, v45
	v_lshlrev_b32_e32 v52, 16, v46
	v_and_b32_e32 v53, 0xffff0000, v46
	v_lshlrev_b32_e32 v46, 16, v47
	v_and_b32_e32 v47, 0xffff0000, v47
	v_pk_add_f32 v[38:39], v[38:39], v[44:45]
	v_pk_add_f32 v[36:37], v[36:37], v[50:51]
	v_pk_add_f32 v[44:45], v[34:35], v[46:47]
	v_pk_add_f32 v[46:47], v[32:33], v[52:53]
	v_mul_f32_e32 v32, v37, v37
	v_mul_f32_e32 v33, v39, v39
	v_mul_f32_e32 v34, v47, v47
	v_mul_f32_e32 v35, v45, v45
	v_fmac_f32_e32 v32, v36, v36
	v_fmac_f32_e32 v33, v38, v38
	v_fmac_f32_e32 v34, v46, v46
	v_fmac_f32_e32 v35, v44, v44
	v_add_f32_e32 v32, v32, v33
	v_add_f32_e32 v33, v34, v35
	v_add_f32_e32 v32, v32, v33
	v_add_f32_e32 v32, v56, v32
	v_mov_b32_e32 v33, v32
	s_nop 1
	v_permlane16_swap_b32_e32 v32, v33
	v_cvt_pk_bf16_f32 v34, v36, v37
	v_cvt_pk_bf16_f32 v35, v38, v39
	v_cvt_pk_bf16_f32 v36, v46, v47
	v_cvt_pk_bf16_f32 v37, v44, v45
	s_waitcnt lgkmcnt(0)
	v_add_f32_e32 v32, v32, v33
	v_mov_b32_e32 v33, v32
	s_nop 1
	v_permlane32_swap_b32_e32 v32, v33
	global_store_dwordx4 v[54:55], v[34:37], off offset:256
	s_and_saveexec_b64 s[44:45], vcc
	s_cbranch_execz .LBB0_1074
	s_waitcnt lgkmcnt(0)
	v_add_f32_e32 v34, v32, v33
	s_lshl_b32 s22, s56, 2
	v_lshlrev_b64 v[32:33], 6, v[48:49]
	s_ashr_i32 s23, s22, 31
	v_lshl_add_u64 v[32:33], s[14:15], 0, v[32:33]
	v_lshl_add_u64 v[32:33], s[22:23], 2, v[32:33]
	s_lshl_b32 s16, s62, 2
	v_lshl_add_u64 v[32:33], v[32:33], 0, s[16:17]
	global_store_dword v[32:33], v34, off
.LBB0_1074:
	s_or_b64 exec, exec, s[44:45]
	v_add_u32_e32 v32, 0xa0, v146
	s_waitcnt lgkmcnt(0)
	v_ashrrev_i32_e32 v33, 31, v32
	v_lshlrev_b64 v[34:35], 11, v[32:33]
	v_lshl_add_u64 v[34:35], s[36:37], 0, v[34:35]
	v_lshl_add_u64 v[38:39], v[144:145], 1, v[34:35]
	s_waitcnt vmcnt(21)
	v_mov_b32_e32 v34, v216
	v_mov_b32_e32 v35, v217
	v_mov_b32_e32 v36, v218
	v_mov_b32_e32 v37, v219
	v_lshlrev_b32_e32 v40, 16, v34
	v_and_b32_e32 v41, 0xffff0000, v34
	v_lshlrev_b32_e32 v34, 16, v35
	v_and_b32_e32 v35, 0xffff0000, v35
	v_lshlrev_b32_e32 v42, 16, v36
	v_and_b32_e32 v43, 0xffff0000, v36
	v_lshlrev_b32_e32 v36, 16, v37
	v_and_b32_e32 v37, 0xffff0000, v37
	v_pk_add_f32 v[34:35], v[30:31], v[34:35]
	v_pk_add_f32 v[40:41], v[28:29], v[40:41]
	v_pk_add_f32 v[36:37], v[26:27], v[36:37]
	v_pk_add_f32 v[42:43], v[24:25], v[42:43]
	v_cvt_pk_bf16_f32 v24, v40, v41
	v_cvt_pk_bf16_f32 v25, v34, v35
	v_mul_f32_e32 v41, v41, v41
	v_cvt_pk_bf16_f32 v26, v42, v43
	v_cvt_pk_bf16_f32 v27, v36, v37
	v_mul_f32_e32 v35, v35, v35
	v_mul_f32_e32 v43, v43, v43
	v_mul_f32_e32 v37, v37, v37
	v_fmac_f32_e32 v41, v40, v40
	v_fmac_f32_e32 v35, v34, v34
	v_fmac_f32_e32 v43, v42, v42
	v_fmac_f32_e32 v37, v36, v36
	v_add_f32_e32 v34, v41, v35
	v_add_f32_e32 v35, v43, v37
	v_add_f32_e32 v40, v34, v35
	global_store_dwordx4 v[38:39], v[24:27], off
	s_waitcnt vmcnt(21)
	v_mov_b32_e32 v28, v220
	v_mov_b32_e32 v29, v221
	v_mov_b32_e32 v30, v222
	v_mov_b32_e32 v31, v223
	v_lshlrev_b32_e32 v34, 16, v28
	v_and_b32_e32 v35, 0xffff0000, v28
	v_lshlrev_b32_e32 v28, 16, v29
	v_and_b32_e32 v29, 0xffff0000, v29
	v_lshlrev_b32_e32 v36, 16, v30
	v_and_b32_e32 v37, 0xffff0000, v30
	v_lshlrev_b32_e32 v30, 16, v31
	v_and_b32_e32 v31, 0xffff0000, v31
	v_pk_add_f32 v[22:23], v[22:23], v[28:29]
	v_pk_add_f32 v[20:21], v[20:21], v[34:35]
	v_pk_add_f32 v[28:29], v[18:19], v[30:31]
	v_pk_add_f32 v[30:31], v[16:17], v[36:37]
	v_mul_f32_e32 v16, v21, v21
	v_mul_f32_e32 v17, v23, v23
	v_mul_f32_e32 v18, v31, v31
	v_mul_f32_e32 v19, v29, v29
	v_fmac_f32_e32 v16, v20, v20
	v_fmac_f32_e32 v17, v22, v22
	v_fmac_f32_e32 v18, v30, v30
	v_fmac_f32_e32 v19, v28, v28
	v_add_f32_e32 v16, v16, v17
	v_add_f32_e32 v17, v18, v19
	v_add_f32_e32 v16, v16, v17
	v_add_f32_e32 v16, v40, v16
	v_mov_b32_e32 v17, v16
	s_nop 1
	v_permlane16_swap_b32_e32 v16, v17
	v_cvt_pk_bf16_f32 v18, v20, v21
	v_cvt_pk_bf16_f32 v19, v22, v23
	v_cvt_pk_bf16_f32 v20, v30, v31
	v_cvt_pk_bf16_f32 v21, v28, v29
	s_waitcnt lgkmcnt(0)
	v_add_f32_e32 v16, v16, v17
	v_mov_b32_e32 v17, v16
	s_nop 1
	v_permlane32_swap_b32_e32 v16, v17
	global_store_dwordx4 v[38:39], v[18:21], off offset:256
	s_and_saveexec_b64 s[44:45], vcc
	s_cbranch_execz .LBB0_1076
	s_waitcnt lgkmcnt(0)
	v_add_f32_e32 v18, v16, v17
	s_lshl_b32 s22, s56, 2
	v_lshlrev_b64 v[16:17], 6, v[32:33]
	s_ashr_i32 s23, s22, 31
	v_lshl_add_u64 v[16:17], s[14:15], 0, v[16:17]
	v_lshl_add_u64 v[16:17], s[22:23], 2, v[16:17]
	s_lshl_b32 s16, s62, 2
	v_lshl_add_u64 v[16:17], v[16:17], 0, s[16:17]
	global_store_dword v[16:17], v18, off
.LBB0_1076:
	s_or_b64 exec, exec, s[44:45]
	v_add_u32_e32 v16, 0xb0, v146
	s_waitcnt lgkmcnt(0)
	v_ashrrev_i32_e32 v17, 31, v16
	v_lshlrev_b64 v[18:19], 11, v[16:17]
	v_lshl_add_u64 v[18:19], s[36:37], 0, v[18:19]
	v_lshl_add_u64 v[22:23], v[144:145], 1, v[18:19]
	s_waitcnt vmcnt(22)
	v_mov_b32_e32 v18, v226
	v_mov_b32_e32 v19, v227
	v_mov_b32_e32 v20, v228
	v_mov_b32_e32 v21, v229
	v_lshlrev_b32_e32 v24, 16, v18
	v_and_b32_e32 v25, 0xffff0000, v18
	v_lshlrev_b32_e32 v18, 16, v19
	v_and_b32_e32 v19, 0xffff0000, v19
	v_lshlrev_b32_e32 v26, 16, v20
	v_and_b32_e32 v27, 0xffff0000, v20
	v_lshlrev_b32_e32 v20, 16, v21
	v_and_b32_e32 v21, 0xffff0000, v21
	v_pk_add_f32 v[18:19], v[14:15], v[18:19]
	v_pk_add_f32 v[24:25], v[12:13], v[24:25]
	v_pk_add_f32 v[20:21], v[10:11], v[20:21]
	v_pk_add_f32 v[26:27], v[8:9], v[26:27]
	v_cvt_pk_bf16_f32 v8, v24, v25
	v_cvt_pk_bf16_f32 v9, v18, v19
	v_mul_f32_e32 v25, v25, v25
	v_cvt_pk_bf16_f32 v10, v26, v27
	v_cvt_pk_bf16_f32 v11, v20, v21
	v_mul_f32_e32 v19, v19, v19
	v_mul_f32_e32 v27, v27, v27
	v_mul_f32_e32 v21, v21, v21
	v_fmac_f32_e32 v25, v24, v24
	v_fmac_f32_e32 v19, v18, v18
	v_fmac_f32_e32 v27, v26, v26
	v_fmac_f32_e32 v21, v20, v20
	v_add_f32_e32 v18, v25, v19
	v_add_f32_e32 v19, v27, v21
	v_add_f32_e32 v24, v18, v19
	global_store_dwordx4 v[22:23], v[8:11], off
	s_waitcnt vmcnt(22)
	v_mov_b32_e32 v12, v230
	v_mov_b32_e32 v13, v231
	v_mov_b32_e32 v14, v232
	v_mov_b32_e32 v15, v233
	v_lshlrev_b32_e32 v18, 16, v12
	v_and_b32_e32 v19, 0xffff0000, v12
	v_lshlrev_b32_e32 v12, 16, v13
	v_and_b32_e32 v13, 0xffff0000, v13
	v_lshlrev_b32_e32 v20, 16, v14
	v_and_b32_e32 v21, 0xffff0000, v14
	v_lshlrev_b32_e32 v14, 16, v15
	v_and_b32_e32 v15, 0xffff0000, v15
	v_pk_add_f32 v[6:7], v[6:7], v[12:13]
	v_pk_add_f32 v[4:5], v[4:5], v[18:19]
	v_pk_add_f32 v[12:13], v[2:3], v[14:15]
	v_pk_add_f32 v[14:15], v[0:1], v[20:21]
	v_mul_f32_e32 v0, v5, v5
	v_mul_f32_e32 v1, v7, v7
	v_mul_f32_e32 v2, v15, v15
	v_mul_f32_e32 v3, v13, v13
	v_fmac_f32_e32 v0, v4, v4
	v_fmac_f32_e32 v1, v6, v6
	v_fmac_f32_e32 v2, v14, v14
	v_fmac_f32_e32 v3, v12, v12
	v_add_f32_e32 v0, v0, v1
	v_add_f32_e32 v1, v2, v3
	v_add_f32_e32 v0, v0, v1
	v_add_f32_e32 v0, v24, v0
	v_mov_b32_e32 v1, v0
	s_nop 1
	v_permlane16_swap_b32_e32 v0, v1
	v_cvt_pk_bf16_f32 v2, v4, v5
	v_cvt_pk_bf16_f32 v3, v6, v7
	v_cvt_pk_bf16_f32 v4, v14, v15
	v_cvt_pk_bf16_f32 v5, v12, v13
	s_waitcnt lgkmcnt(0)
	v_add_f32_e32 v0, v0, v1
	v_mov_b32_e32 v1, v0
	s_nop 1
	v_permlane32_swap_b32_e32 v0, v1
	global_store_dwordx4 v[22:23], v[2:5], off offset:256
	s_and_saveexec_b64 s[44:45], vcc
	s_cbranch_execz .LBB0_1078
	s_waitcnt lgkmcnt(0)
	v_add_f32_e32 v2, v0, v1
	s_lshl_b32 s22, s56, 2
	v_lshlrev_b64 v[0:1], 6, v[16:17]
	s_ashr_i32 s23, s22, 31
	v_lshl_add_u64 v[0:1], s[14:15], 0, v[0:1]
	v_lshl_add_u64 v[0:1], s[22:23], 2, v[0:1]
	s_lshl_b32 s16, s62, 2
	v_lshl_add_u64 v[0:1], v[0:1], 0, s[16:17]
	global_store_dword v[0:1], v2, off

.LBB0_1606:
	s_lshl_b32 s16, s16, 8
	v_mov_b32_e32 v166, v149
	v_mov_b32_e32 v167, v148
	s_add_i32 s16, s16, s61
	s_lshl_b32 s26, s14, 8
	v_add_u32_e32 v146, s16, v166
	s_or_b32 s26, s26, s62
	v_ashrrev_i32_e32 v147, 31, v146
	v_lshl_add_u32 v144, v167, 3, s26
	v_lshlrev_b64 v[154:155], 11, v[146:147]
	v_ashrrev_i32_e32 v145, 31, v144
	v_lshl_add_u64 v[154:155], s[20:21], 0, v[154:155]
	v_lshl_add_u64 v[158:159], v[144:145], 1, v[154:155]
	v_mov_b32_e32 v236, 0x8000
	v_mov_b32_e32 v237, 0
	v_mov_b32_e32 v238, 0x28000
	v_mov_b32_e32 v239, 0
	global_load_dwordx4 v[168:171], v[158:159], off
	global_load_dwordx4 v[172:175], v[158:159], off offset:256
	v_lshl_add_u64 v[234:235], v[158:159], 0, v[236:237]
	global_load_dwordx4 v[176:179], v[234:235], off
	global_load_dwordx4 v[180:183], v[234:235], off offset:256
	v_lshl_add_u64 v[234:235], v[234:235], 0, v[236:237]
	global_load_dwordx4 v[184:187], v[234:235], off
	global_load_dwordx4 v[188:191], v[234:235], off offset:256
	v_lshl_add_u64 v[234:235], v[234:235], 0, v[236:237]
	global_load_dwordx4 v[192:195], v[234:235], off
	global_load_dwordx4 v[196:199], v[234:235], off offset:256
	v_lshl_add_u64 v[234:235], v[234:235], 0, v[238:239]
	global_load_dwordx4 v[200:203], v[234:235], off
	global_load_dwordx4 v[204:207], v[234:235], off offset:256
	v_lshl_add_u64 v[234:235], v[234:235], 0, v[236:237]
	global_load_dwordx4 v[208:211], v[234:235], off
	global_load_dwordx4 v[212:215], v[234:235], off offset:256
	v_lshl_add_u64 v[234:235], v[234:235], 0, v[236:237]
	global_load_dwordx4 v[216:219], v[234:235], off
	global_load_dwordx4 v[220:223], v[234:235], off offset:256
	v_lshl_add_u64 v[234:235], v[234:235], 0, v[236:237]
	global_load_dwordx4 v[226:229], v[234:235], off
	global_load_dwordx4 v[230:233], v[234:235], off offset:256
	v_cmp_eq_u32_e32 vcc, 0, v167
	s_waitcnt vmcnt(15)
	v_mov_b32_e32 v154, v168
	v_mov_b32_e32 v155, v169
	v_mov_b32_e32 v156, v170
	v_mov_b32_e32 v157, v171
	v_lshlrev_b32_e32 v160, 16, v154
	v_and_b32_e32 v161, 0xffff0000, v154
	v_lshlrev_b32_e32 v154, 16, v155
	v_and_b32_e32 v155, 0xffff0000, v155
	v_lshlrev_b32_e32 v162, 16, v156
	v_and_b32_e32 v163, 0xffff0000, v156
	v_lshlrev_b32_e32 v156, 16, v157
	v_and_b32_e32 v157, 0xffff0000, v157
	v_pk_add_f32 v[126:127], v[126:127], v[154:155]
	v_pk_add_f32 v[160:161], v[124:125], v[160:161]
	v_pk_add_f32 v[164:165], v[122:123], v[156:157]
	v_pk_add_f32 v[162:163], v[120:121], v[162:163]
	v_cvt_pk_bf16_f32 v122, v160, v161
	v_cvt_pk_bf16_f32 v123, v126, v127
	v_mul_f32_e32 v161, v161, v161
	v_cvt_pk_bf16_f32 v124, v162, v163
	v_cvt_pk_bf16_f32 v125, v164, v165
	v_mul_f32_e32 v127, v127, v127
	v_mul_f32_e32 v163, v163, v163
	v_mul_f32_e32 v165, v165, v165
	v_fmac_f32_e32 v161, v160, v160
	v_fmac_f32_e32 v127, v126, v126
	v_fmac_f32_e32 v163, v162, v162
	v_fmac_f32_e32 v165, v164, v164
	v_add_f32_e32 v126, v161, v127
	v_add_f32_e32 v127, v163, v165
	v_add_f32_e32 v162, v126, v127
	v_lshlrev_b32_e32 v120, 2, v166
	v_lshl_add_u32 v121, v167, 6, v120
	v_xor_b32_e32 v120, 64, v121
	global_store_dwordx4 v[158:159], v[122:125], off
	s_waitcnt vmcnt(15)
	v_mov_b32_e32 v154, v172
	v_mov_b32_e32 v155, v173
	v_mov_b32_e32 v156, v174
	v_mov_b32_e32 v157, v175
	v_lshlrev_b32_e32 v126, 16, v154
	v_and_b32_e32 v127, 0xffff0000, v154
	v_lshlrev_b32_e32 v154, 16, v155
	v_and_b32_e32 v155, 0xffff0000, v155
	v_lshlrev_b32_e32 v160, 16, v156
	v_and_b32_e32 v161, 0xffff0000, v156
	v_lshlrev_b32_e32 v156, 16, v157
	v_and_b32_e32 v157, 0xffff0000, v157
	v_pk_add_f32 v[118:119], v[118:119], v[154:155]
	v_pk_add_f32 v[116:117], v[116:117], v[126:127]
	v_pk_add_f32 v[126:127], v[114:115], v[156:157]
	v_pk_add_f32 v[154:155], v[112:113], v[160:161]
	v_mul_f32_e32 v112, v117, v117
	v_mul_f32_e32 v113, v119, v119
	v_mul_f32_e32 v114, v155, v155
	v_mul_f32_e32 v115, v127, v127
	v_fmac_f32_e32 v112, v116, v116
	v_fmac_f32_e32 v113, v118, v118
	v_fmac_f32_e32 v114, v154, v154
	v_fmac_f32_e32 v115, v126, v126
	v_add_f32_e32 v112, v112, v113
	v_add_f32_e32 v113, v114, v115
	v_add_f32_e32 v112, v112, v113
	v_add_f32_e32 v112, v162, v112
	v_mov_b32_e32 v113, v112
	s_nop 1
	v_permlane16_swap_b32_e32 v112, v113
	v_xor_b32_e32 v114, 0x80, v121
	v_cvt_pk_bf16_f32 v116, v116, v117
	v_cvt_pk_bf16_f32 v117, v118, v119
	v_cvt_pk_bf16_f32 v118, v154, v155
	s_waitcnt lgkmcnt(0)
	v_add_f32_e32 v112, v112, v113
	v_mov_b32_e32 v113, v112
	s_nop 1
	v_permlane32_swap_b32_e32 v112, v113
	v_cvt_pk_bf16_f32 v119, v126, v127
	global_store_dwordx4 v[158:159], v[116:119], off offset:256
	s_and_saveexec_b64 s[46:47], vcc
	s_cbranch_execz .LBB0_1608
	s_waitcnt lgkmcnt(0)
	v_add_f32_e32 v115, v112, v113
	s_lshl_b32 s26, s14, 2
	v_lshlrev_b64 v[112:113], 6, v[146:147]
	s_ashr_i32 s27, s26, 31
	v_lshl_add_u64 v[112:113], s[12:13], 0, v[112:113]
	v_lshl_add_u64 v[112:113], s[26:27], 2, v[112:113]
	s_lshl_b32 s16, s60, 2
	v_lshl_add_u64 v[112:113], v[112:113], 0, s[16:17]
	global_store_dword v[112:113], v115, off
.LBB0_1608:
	s_or_b64 exec, exec, s[46:47]
	v_add_u32_e32 v112, 16, v146
	s_waitcnt lgkmcnt(0)
	v_ashrrev_i32_e32 v113, 31, v112
	v_lshlrev_b64 v[116:117], 11, v[112:113]
	v_lshl_add_u64 v[116:117], s[20:21], 0, v[116:117]
	v_lshl_add_u64 v[122:123], v[144:145], 1, v[116:117]
	s_waitcnt vmcnt(16)
	v_mov_b32_e32 v116, v176
	v_mov_b32_e32 v117, v177
	v_mov_b32_e32 v118, v178
	v_mov_b32_e32 v119, v179
	v_lshlrev_b32_e32 v124, 16, v116
	v_and_b32_e32 v125, 0xffff0000, v116
	v_lshlrev_b32_e32 v116, 16, v117
	v_and_b32_e32 v117, 0xffff0000, v117
	v_lshlrev_b32_e32 v126, 16, v118
	v_and_b32_e32 v127, 0xffff0000, v118
	v_lshlrev_b32_e32 v118, 16, v119
	v_and_b32_e32 v119, 0xffff0000, v119
	v_pk_add_f32 v[116:117], v[110:111], v[116:117]
	v_pk_add_f32 v[124:125], v[108:109], v[124:125]
	v_pk_add_f32 v[118:119], v[106:107], v[118:119]
	v_pk_add_f32 v[126:127], v[104:105], v[126:127]
	v_cvt_pk_bf16_f32 v104, v124, v125
	v_cvt_pk_bf16_f32 v105, v116, v117
	v_mul_f32_e32 v115, v125, v125
	v_cvt_pk_bf16_f32 v106, v126, v127
	v_cvt_pk_bf16_f32 v107, v118, v119
	v_mul_f32_e32 v117, v117, v117
	v_mul_f32_e32 v121, v127, v127
	v_mul_f32_e32 v119, v119, v119
	v_fmac_f32_e32 v115, v124, v124
	v_fmac_f32_e32 v117, v116, v116
	v_fmac_f32_e32 v121, v126, v126
	v_fmac_f32_e32 v119, v118, v118
	v_add_f32_e32 v115, v115, v117
	v_add_f32_e32 v116, v121, v119
	v_add_f32_e32 v115, v115, v116
	global_store_dwordx4 v[122:123], v[104:107], off
	s_waitcnt vmcnt(16)
	v_mov_b32_e32 v108, v180
	v_mov_b32_e32 v109, v181
	v_mov_b32_e32 v110, v182
	v_mov_b32_e32 v111, v183
	v_lshlrev_b32_e32 v116, 16, v108
	v_and_b32_e32 v117, 0xffff0000, v108
	v_lshlrev_b32_e32 v108, 16, v109
	v_and_b32_e32 v109, 0xffff0000, v109
	v_lshlrev_b32_e32 v118, 16, v110
	v_and_b32_e32 v119, 0xffff0000, v110
	v_lshlrev_b32_e32 v110, 16, v111
	v_and_b32_e32 v111, 0xffff0000, v111
	v_pk_add_f32 v[102:103], v[102:103], v[108:109]
	v_pk_add_f32 v[100:101], v[100:101], v[116:117]
	v_pk_add_f32 v[108:109], v[98:99], v[110:111]
	v_pk_add_f32 v[110:111], v[96:97], v[118:119]
	v_mul_f32_e32 v96, v101, v101
	v_mul_f32_e32 v97, v103, v103
	v_mul_f32_e32 v98, v111, v111
	v_mul_f32_e32 v99, v109, v109
	v_fmac_f32_e32 v96, v100, v100
	v_fmac_f32_e32 v97, v102, v102
	v_fmac_f32_e32 v98, v110, v110
	v_fmac_f32_e32 v99, v108, v108
	v_add_f32_e32 v96, v96, v97
	v_add_f32_e32 v97, v98, v99
	v_add_f32_e32 v96, v96, v97
	v_add_f32_e32 v96, v115, v96
	v_mov_b32_e32 v97, v96
	s_nop 1
	v_permlane16_swap_b32_e32 v96, v97
	v_cvt_pk_bf16_f32 v98, v100, v101
	v_cvt_pk_bf16_f32 v99, v102, v103
	v_cvt_pk_bf16_f32 v100, v110, v111
	v_cvt_pk_bf16_f32 v101, v108, v109
	s_waitcnt lgkmcnt(0)
	v_add_f32_e32 v96, v96, v97
	v_mov_b32_e32 v97, v96
	s_nop 1
	v_permlane32_swap_b32_e32 v96, v97
	global_store_dwordx4 v[122:123], v[98:101], off offset:256
	s_and_saveexec_b64 s[46:47], vcc
	s_cbranch_execz .LBB0_1610
	s_waitcnt lgkmcnt(0)
	v_add_f32_e32 v98, v96, v97
	s_lshl_b32 s26, s14, 2
	v_lshlrev_b64 v[96:97], 6, v[112:113]
	s_ashr_i32 s27, s26, 31
	v_lshl_add_u64 v[96:97], s[12:13], 0, v[96:97]
	v_lshl_add_u64 v[96:97], s[26:27], 2, v[96:97]
	s_lshl_b32 s16, s60, 2
	v_lshl_add_u64 v[96:97], v[96:97], 0, s[16:17]
	global_store_dword v[96:97], v98, off
.LBB0_1610:
	s_or_b64 exec, exec, s[46:47]
	v_add_u32_e32 v96, 32, v146
	s_waitcnt lgkmcnt(0)
	v_ashrrev_i32_e32 v97, 31, v96
	v_lshlrev_b64 v[98:99], 11, v[96:97]
	v_lshl_add_u64 v[98:99], s[20:21], 0, v[98:99]
	v_lshl_add_u64 v[102:103], v[144:145], 1, v[98:99]
	s_waitcnt vmcnt(17)
	v_mov_b32_e32 v98, v184
	v_mov_b32_e32 v99, v185
	v_mov_b32_e32 v100, v186
	v_mov_b32_e32 v101, v187
	v_lshlrev_b32_e32 v104, 16, v98
	v_and_b32_e32 v105, 0xffff0000, v98
	v_lshlrev_b32_e32 v98, 16, v99
	v_and_b32_e32 v99, 0xffff0000, v99
	v_lshlrev_b32_e32 v106, 16, v100
	v_and_b32_e32 v107, 0xffff0000, v100
	v_lshlrev_b32_e32 v100, 16, v101
	v_and_b32_e32 v101, 0xffff0000, v101
	v_pk_add_f32 v[98:99], v[94:95], v[98:99]
	v_pk_add_f32 v[104:105], v[92:93], v[104:105]
	v_pk_add_f32 v[100:101], v[90:91], v[100:101]
	v_pk_add_f32 v[106:107], v[88:89], v[106:107]
	v_cvt_pk_bf16_f32 v88, v104, v105
	v_cvt_pk_bf16_f32 v89, v98, v99
	v_mul_f32_e32 v105, v105, v105
	v_cvt_pk_bf16_f32 v90, v106, v107
	v_cvt_pk_bf16_f32 v91, v100, v101
	v_mul_f32_e32 v99, v99, v99
	v_mul_f32_e32 v107, v107, v107
	v_mul_f32_e32 v101, v101, v101
	v_fmac_f32_e32 v105, v104, v104
	v_fmac_f32_e32 v99, v98, v98
	v_fmac_f32_e32 v107, v106, v106
	v_fmac_f32_e32 v101, v100, v100
	v_add_f32_e32 v98, v105, v99
	v_add_f32_e32 v99, v107, v101
	v_add_f32_e32 v104, v98, v99
	global_store_dwordx4 v[102:103], v[88:91], off
	s_waitcnt vmcnt(17)
	v_mov_b32_e32 v92, v188
	v_mov_b32_e32 v93, v189
	v_mov_b32_e32 v94, v190
	v_mov_b32_e32 v95, v191
	v_lshlrev_b32_e32 v98, 16, v92
	v_and_b32_e32 v99, 0xffff0000, v92
	v_lshlrev_b32_e32 v92, 16, v93
	v_and_b32_e32 v93, 0xffff0000, v93
	v_lshlrev_b32_e32 v100, 16, v94
	v_and_b32_e32 v101, 0xffff0000, v94
	v_lshlrev_b32_e32 v94, 16, v95
	v_and_b32_e32 v95, 0xffff0000, v95
	v_pk_add_f32 v[86:87], v[86:87], v[92:93]
	v_pk_add_f32 v[84:85], v[84:85], v[98:99]
	v_pk_add_f32 v[92:93], v[82:83], v[94:95]
	v_pk_add_f32 v[94:95], v[80:81], v[100:101]
	v_mul_f32_e32 v80, v85, v85
	v_mul_f32_e32 v81, v87, v87
	v_mul_f32_e32 v82, v95, v95
	v_mul_f32_e32 v83, v93, v93
	v_fmac_f32_e32 v80, v84, v84
	v_fmac_f32_e32 v81, v86, v86
	v_fmac_f32_e32 v82, v94, v94
	v_fmac_f32_e32 v83, v92, v92
	v_add_f32_e32 v80, v80, v81
	v_add_f32_e32 v81, v82, v83
	v_add_f32_e32 v80, v80, v81
	v_add_f32_e32 v80, v104, v80
	v_mov_b32_e32 v81, v80
	s_nop 1
	v_permlane16_swap_b32_e32 v80, v81
	v_cvt_pk_bf16_f32 v82, v84, v85
	v_cvt_pk_bf16_f32 v83, v86, v87
	v_cvt_pk_bf16_f32 v84, v94, v95
	v_cvt_pk_bf16_f32 v85, v92, v93
	s_waitcnt lgkmcnt(0)
	v_add_f32_e32 v80, v80, v81
	v_mov_b32_e32 v81, v80
	s_nop 1
	v_permlane32_swap_b32_e32 v80, v81
	global_store_dwordx4 v[102:103], v[82:85], off offset:256
	s_and_saveexec_b64 s[46:47], vcc
	s_cbranch_execz .LBB0_1612
	s_waitcnt lgkmcnt(0)
	v_add_f32_e32 v82, v80, v81
	s_lshl_b32 s26, s14, 2
	v_lshlrev_b64 v[80:81], 6, v[96:97]
	s_ashr_i32 s27, s26, 31
	v_lshl_add_u64 v[80:81], s[12:13], 0, v[80:81]
	v_lshl_add_u64 v[80:81], s[26:27], 2, v[80:81]
	s_lshl_b32 s16, s60, 2
	v_lshl_add_u64 v[80:81], v[80:81], 0, s[16:17]
	global_store_dword v[80:81], v82, off
.LBB0_1612:
	s_or_b64 exec, exec, s[46:47]
	v_add_u32_e32 v80, 48, v146
	s_waitcnt lgkmcnt(0)
	v_ashrrev_i32_e32 v81, 31, v80
	v_lshlrev_b64 v[82:83], 11, v[80:81]
	v_lshl_add_u64 v[82:83], s[20:21], 0, v[82:83]
	v_lshl_add_u64 v[86:87], v[144:145], 1, v[82:83]
	s_waitcnt vmcnt(18)
	v_mov_b32_e32 v82, v192
	v_mov_b32_e32 v83, v193
	v_mov_b32_e32 v84, v194
	v_mov_b32_e32 v85, v195
	v_lshlrev_b32_e32 v88, 16, v82
	v_and_b32_e32 v89, 0xffff0000, v82
	v_lshlrev_b32_e32 v82, 16, v83
	v_and_b32_e32 v83, 0xffff0000, v83
	v_lshlrev_b32_e32 v90, 16, v84
	v_and_b32_e32 v91, 0xffff0000, v84
	v_lshlrev_b32_e32 v84, 16, v85
	v_and_b32_e32 v85, 0xffff0000, v85
	v_pk_add_f32 v[82:83], v[78:79], v[82:83]
	v_pk_add_f32 v[88:89], v[76:77], v[88:89]
	v_pk_add_f32 v[84:85], v[74:75], v[84:85]
	v_pk_add_f32 v[90:91], v[72:73], v[90:91]
	v_cvt_pk_bf16_f32 v72, v88, v89
	v_cvt_pk_bf16_f32 v73, v82, v83
	v_mul_f32_e32 v89, v89, v89
	v_cvt_pk_bf16_f32 v74, v90, v91
	v_cvt_pk_bf16_f32 v75, v84, v85
	v_mul_f32_e32 v83, v83, v83
	v_mul_f32_e32 v91, v91, v91
	v_mul_f32_e32 v85, v85, v85
	v_fmac_f32_e32 v89, v88, v88
	v_fmac_f32_e32 v83, v82, v82
	v_fmac_f32_e32 v91, v90, v90
	v_fmac_f32_e32 v85, v84, v84
	v_add_f32_e32 v82, v89, v83
	v_add_f32_e32 v83, v91, v85
	v_add_f32_e32 v88, v82, v83
	global_store_dwordx4 v[86:87], v[72:75], off
	s_waitcnt vmcnt(18)
	v_mov_b32_e32 v76, v196
	v_mov_b32_e32 v77, v197
	v_mov_b32_e32 v78, v198
	v_mov_b32_e32 v79, v199
	v_lshlrev_b32_e32 v82, 16, v76
	v_and_b32_e32 v83, 0xffff0000, v76
	v_lshlrev_b32_e32 v76, 16, v77
	v_and_b32_e32 v77, 0xffff0000, v77
	v_lshlrev_b32_e32 v84, 16, v78
	v_and_b32_e32 v85, 0xffff0000, v78
	v_lshlrev_b32_e32 v78, 16, v79
	v_and_b32_e32 v79, 0xffff0000, v79
	v_pk_add_f32 v[70:71], v[70:71], v[76:77]
	v_pk_add_f32 v[68:69], v[68:69], v[82:83]
	v_pk_add_f32 v[76:77], v[66:67], v[78:79]
	v_pk_add_f32 v[78:79], v[64:65], v[84:85]
	v_mul_f32_e32 v64, v69, v69
	v_mul_f32_e32 v65, v71, v71
	v_mul_f32_e32 v66, v79, v79
	v_mul_f32_e32 v67, v77, v77
	v_fmac_f32_e32 v64, v68, v68
	v_fmac_f32_e32 v65, v70, v70
	v_fmac_f32_e32 v66, v78, v78
	v_fmac_f32_e32 v67, v76, v76
	v_add_f32_e32 v64, v64, v65
	v_add_f32_e32 v65, v66, v67
	v_add_f32_e32 v64, v64, v65
	v_add_f32_e32 v64, v88, v64
	v_mov_b32_e32 v65, v64
	s_nop 1
	v_permlane16_swap_b32_e32 v64, v65
	v_cvt_pk_bf16_f32 v66, v68, v69
	v_cvt_pk_bf16_f32 v67, v70, v71
	v_cvt_pk_bf16_f32 v68, v78, v79
	v_cvt_pk_bf16_f32 v69, v76, v77
	s_waitcnt lgkmcnt(0)
	v_add_f32_e32 v64, v64, v65
	v_mov_b32_e32 v65, v64
	s_nop 1
	v_permlane32_swap_b32_e32 v64, v65
	global_store_dwordx4 v[86:87], v[66:69], off offset:256
	s_and_saveexec_b64 s[46:47], vcc
	s_cbranch_execz .LBB0_1614
	s_waitcnt lgkmcnt(0)
	v_add_f32_e32 v66, v64, v65
	s_lshl_b32 s26, s14, 2
	v_lshlrev_b64 v[64:65], 6, v[80:81]
	s_ashr_i32 s27, s26, 31
	v_lshl_add_u64 v[64:65], s[12:13], 0, v[64:65]
	v_lshl_add_u64 v[64:65], s[26:27], 2, v[64:65]
	s_lshl_b32 s16, s60, 2
	v_lshl_add_u64 v[64:65], v[64:65], 0, s[16:17]
	global_store_dword v[64:65], v66, off
.LBB0_1614:
	s_or_b64 exec, exec, s[46:47]
	v_add_u32_e32 v64, 0x80, v146
	s_waitcnt lgkmcnt(0)
	v_ashrrev_i32_e32 v65, 31, v64
	v_lshlrev_b64 v[66:67], 11, v[64:65]
	v_lshl_add_u64 v[66:67], s[20:21], 0, v[66:67]
	v_lshl_add_u64 v[70:71], v[144:145], 1, v[66:67]
	s_waitcnt vmcnt(19)
	v_mov_b32_e32 v66, v200
	v_mov_b32_e32 v67, v201
	v_mov_b32_e32 v68, v202
	v_mov_b32_e32 v69, v203
	v_lshlrev_b32_e32 v72, 16, v66
	v_and_b32_e32 v73, 0xffff0000, v66
	v_lshlrev_b32_e32 v66, 16, v67
	v_and_b32_e32 v67, 0xffff0000, v67
	v_lshlrev_b32_e32 v74, 16, v68
	v_and_b32_e32 v75, 0xffff0000, v68
	v_lshlrev_b32_e32 v68, 16, v69
	v_and_b32_e32 v69, 0xffff0000, v69
	v_pk_add_f32 v[66:67], v[62:63], v[66:67]
	v_pk_add_f32 v[72:73], v[60:61], v[72:73]
	v_pk_add_f32 v[68:69], v[58:59], v[68:69]
	v_pk_add_f32 v[74:75], v[56:57], v[74:75]
	v_cvt_pk_bf16_f32 v56, v72, v73
	v_cvt_pk_bf16_f32 v57, v66, v67
	v_mul_f32_e32 v73, v73, v73
	v_cvt_pk_bf16_f32 v58, v74, v75
	v_cvt_pk_bf16_f32 v59, v68, v69
	v_mul_f32_e32 v67, v67, v67
	v_mul_f32_e32 v75, v75, v75
	v_mul_f32_e32 v69, v69, v69
	v_fmac_f32_e32 v73, v72, v72
	v_fmac_f32_e32 v67, v66, v66
	v_fmac_f32_e32 v75, v74, v74
	v_fmac_f32_e32 v69, v68, v68
	v_add_f32_e32 v66, v73, v67
	v_add_f32_e32 v67, v75, v69
	v_add_f32_e32 v72, v66, v67
	global_store_dwordx4 v[70:71], v[56:59], off
	s_waitcnt vmcnt(19)
	v_mov_b32_e32 v60, v204
	v_mov_b32_e32 v61, v205
	v_mov_b32_e32 v62, v206
	v_mov_b32_e32 v63, v207
	v_lshlrev_b32_e32 v66, 16, v60
	v_and_b32_e32 v67, 0xffff0000, v60
	v_lshlrev_b32_e32 v60, 16, v61
	v_and_b32_e32 v61, 0xffff0000, v61
	v_lshlrev_b32_e32 v68, 16, v62
	v_and_b32_e32 v69, 0xffff0000, v62
	v_lshlrev_b32_e32 v62, 16, v63
	v_and_b32_e32 v63, 0xffff0000, v63
	v_pk_add_f32 v[54:55], v[54:55], v[60:61]
	v_pk_add_f32 v[52:53], v[52:53], v[66:67]
	v_pk_add_f32 v[60:61], v[50:51], v[62:63]
	v_pk_add_f32 v[62:63], v[48:49], v[68:69]
	v_mul_f32_e32 v48, v53, v53
	v_mul_f32_e32 v49, v55, v55
	v_mul_f32_e32 v50, v63, v63
	v_mul_f32_e32 v51, v61, v61
	v_fmac_f32_e32 v48, v52, v52
	v_fmac_f32_e32 v49, v54, v54
	v_fmac_f32_e32 v50, v62, v62
	v_fmac_f32_e32 v51, v60, v60
	v_add_f32_e32 v48, v48, v49
	v_add_f32_e32 v49, v50, v51
	v_add_f32_e32 v48, v48, v49
	v_add_f32_e32 v48, v72, v48
	v_mov_b32_e32 v49, v48
	s_nop 1
	v_permlane16_swap_b32_e32 v48, v49
	v_cvt_pk_bf16_f32 v50, v52, v53
	v_cvt_pk_bf16_f32 v51, v54, v55
	v_cvt_pk_bf16_f32 v52, v62, v63
	v_cvt_pk_bf16_f32 v53, v60, v61
	s_waitcnt lgkmcnt(0)
	v_add_f32_e32 v48, v48, v49
	v_mov_b32_e32 v49, v48
	s_nop 1
	v_permlane32_swap_b32_e32 v48, v49
	global_store_dwordx4 v[70:71], v[50:53], off offset:256
	s_and_saveexec_b64 s[46:47], vcc
	s_cbranch_execz .LBB0_1616
	s_waitcnt lgkmcnt(0)
	v_add_f32_e32 v50, v48, v49
	s_lshl_b32 s26, s14, 2
	v_lshlrev_b64 v[48:49], 6, v[64:65]
	s_ashr_i32 s27, s26, 31
	v_lshl_add_u64 v[48:49], s[12:13], 0, v[48:49]
	v_lshl_add_u64 v[48:49], s[26:27], 2, v[48:49]
	s_lshl_b32 s16, s60, 2
	v_lshl_add_u64 v[48:49], v[48:49], 0, s[16:17]
	global_store_dword v[48:49], v50, off
.LBB0_1616:
	s_or_b64 exec, exec, s[46:47]
	v_add_u32_e32 v48, 0x90, v146
	s_waitcnt lgkmcnt(0)
	v_ashrrev_i32_e32 v49, 31, v48
	v_lshlrev_b64 v[50:51], 11, v[48:49]
	v_lshl_add_u64 v[50:51], s[20:21], 0, v[50:51]
	v_lshl_add_u64 v[54:55], v[144:145], 1, v[50:51]
	s_waitcnt vmcnt(20)
	v_mov_b32_e32 v50, v208
	v_mov_b32_e32 v51, v209
	v_mov_b32_e32 v52, v210
	v_mov_b32_e32 v53, v211
	v_lshlrev_b32_e32 v56, 16, v50
	v_and_b32_e32 v57, 0xffff0000, v50
	v_lshlrev_b32_e32 v50, 16, v51
	v_and_b32_e32 v51, 0xffff0000, v51
	v_lshlrev_b32_e32 v58, 16, v52
	v_and_b32_e32 v59, 0xffff0000, v52
	v_lshlrev_b32_e32 v52, 16, v53
	v_and_b32_e32 v53, 0xffff0000, v53
	v_pk_add_f32 v[50:51], v[46:47], v[50:51]
	v_pk_add_f32 v[56:57], v[44:45], v[56:57]
	v_pk_add_f32 v[52:53], v[42:43], v[52:53]
	v_pk_add_f32 v[58:59], v[40:41], v[58:59]
	v_cvt_pk_bf16_f32 v40, v56, v57
	v_cvt_pk_bf16_f32 v41, v50, v51
	v_mul_f32_e32 v57, v57, v57
	v_cvt_pk_bf16_f32 v42, v58, v59
	v_cvt_pk_bf16_f32 v43, v52, v53
	v_mul_f32_e32 v51, v51, v51
	v_mul_f32_e32 v59, v59, v59
	v_mul_f32_e32 v53, v53, v53
	v_fmac_f32_e32 v57, v56, v56
	v_fmac_f32_e32 v51, v50, v50
	v_fmac_f32_e32 v59, v58, v58
	v_fmac_f32_e32 v53, v52, v52
	v_add_f32_e32 v50, v57, v51
	v_add_f32_e32 v51, v59, v53
	v_add_f32_e32 v56, v50, v51
	global_store_dwordx4 v[54:55], v[40:43], off
	s_waitcnt vmcnt(20)
	v_mov_b32_e32 v44, v212
	v_mov_b32_e32 v45, v213
	v_mov_b32_e32 v46, v214
	v_mov_b32_e32 v47, v215
	v_lshlrev_b32_e32 v50, 16, v44
	v_and_b32_e32 v51, 0xffff0000, v44
	v_lshlrev_b32_e32 v44, 16, v45
	v_and_b32_e32 v45, 0xffff0000, v45
	v_lshlrev_b32_e32 v52, 16, v46
	v_and_b32_e32 v53, 0xffff0000, v46
	v_lshlrev_b32_e32 v46, 16, v47
	v_and_b32_e32 v47, 0xffff0000, v47
	v_pk_add_f32 v[38:39], v[38:39], v[44:45]
	v_pk_add_f32 v[36:37], v[36:37], v[50:51]
	v_pk_add_f32 v[44:45], v[34:35], v[46:47]
	v_pk_add_f32 v[46:47], v[32:33], v[52:53]
	v_mul_f32_e32 v32, v37, v37
	v_mul_f32_e32 v33, v39, v39
	v_mul_f32_e32 v34, v47, v47
	v_mul_f32_e32 v35, v45, v45
	v_fmac_f32_e32 v32, v36, v36
	v_fmac_f32_e32 v33, v38, v38
	v_fmac_f32_e32 v34, v46, v46
	v_fmac_f32_e32 v35, v44, v44
	v_add_f32_e32 v32, v32, v33
	v_add_f32_e32 v33, v34, v35
	v_add_f32_e32 v32, v32, v33
	v_add_f32_e32 v32, v56, v32
	v_mov_b32_e32 v33, v32
	s_nop 1
	v_permlane16_swap_b32_e32 v32, v33
	v_cvt_pk_bf16_f32 v34, v36, v37
	v_cvt_pk_bf16_f32 v35, v38, v39
	v_cvt_pk_bf16_f32 v36, v46, v47
	v_cvt_pk_bf16_f32 v37, v44, v45
	s_waitcnt lgkmcnt(0)
	v_add_f32_e32 v32, v32, v33
	v_mov_b32_e32 v33, v32
	s_nop 1
	v_permlane32_swap_b32_e32 v32, v33
	global_store_dwordx4 v[54:55], v[34:37], off offset:256
	s_and_saveexec_b64 s[46:47], vcc
	s_cbranch_execz .LBB0_1618
	s_waitcnt lgkmcnt(0)
	v_add_f32_e32 v34, v32, v33
	s_lshl_b32 s26, s14, 2
	v_lshlrev_b64 v[32:33], 6, v[48:49]
	s_ashr_i32 s27, s26, 31
	v_lshl_add_u64 v[32:33], s[12:13], 0, v[32:33]
	v_lshl_add_u64 v[32:33], s[26:27], 2, v[32:33]
	s_lshl_b32 s16, s60, 2
	v_lshl_add_u64 v[32:33], v[32:33], 0, s[16:17]
	global_store_dword v[32:33], v34, off
.LBB0_1618:
	s_or_b64 exec, exec, s[46:47]
	v_add_u32_e32 v32, 0xa0, v146
	s_waitcnt lgkmcnt(0)
	v_ashrrev_i32_e32 v33, 31, v32
	v_lshlrev_b64 v[34:35], 11, v[32:33]
	v_lshl_add_u64 v[34:35], s[20:21], 0, v[34:35]
	v_lshl_add_u64 v[38:39], v[144:145], 1, v[34:35]
	s_waitcnt vmcnt(21)
	v_mov_b32_e32 v34, v216
	v_mov_b32_e32 v35, v217
	v_mov_b32_e32 v36, v218
	v_mov_b32_e32 v37, v219
	v_lshlrev_b32_e32 v40, 16, v34
	v_and_b32_e32 v41, 0xffff0000, v34
	v_lshlrev_b32_e32 v34, 16, v35
	v_and_b32_e32 v35, 0xffff0000, v35
	v_lshlrev_b32_e32 v42, 16, v36
	v_and_b32_e32 v43, 0xffff0000, v36
	v_lshlrev_b32_e32 v36, 16, v37
	v_and_b32_e32 v37, 0xffff0000, v37
	v_pk_add_f32 v[34:35], v[30:31], v[34:35]
	v_pk_add_f32 v[40:41], v[28:29], v[40:41]
	v_pk_add_f32 v[36:37], v[26:27], v[36:37]
	v_pk_add_f32 v[42:43], v[24:25], v[42:43]
	v_cvt_pk_bf16_f32 v24, v40, v41
	v_cvt_pk_bf16_f32 v25, v34, v35
	v_mul_f32_e32 v41, v41, v41
	v_cvt_pk_bf16_f32 v26, v42, v43
	v_cvt_pk_bf16_f32 v27, v36, v37
	v_mul_f32_e32 v35, v35, v35
	v_mul_f32_e32 v43, v43, v43
	v_mul_f32_e32 v37, v37, v37
	v_fmac_f32_e32 v41, v40, v40
	v_fmac_f32_e32 v35, v34, v34
	v_fmac_f32_e32 v43, v42, v42
	v_fmac_f32_e32 v37, v36, v36
	v_add_f32_e32 v34, v41, v35
	v_add_f32_e32 v35, v43, v37
	v_add_f32_e32 v40, v34, v35
	global_store_dwordx4 v[38:39], v[24:27], off
	s_waitcnt vmcnt(21)
	v_mov_b32_e32 v28, v220
	v_mov_b32_e32 v29, v221
	v_mov_b32_e32 v30, v222
	v_mov_b32_e32 v31, v223
	v_lshlrev_b32_e32 v34, 16, v28
	v_and_b32_e32 v35, 0xffff0000, v28
	v_lshlrev_b32_e32 v28, 16, v29
	v_and_b32_e32 v29, 0xffff0000, v29
	v_lshlrev_b32_e32 v36, 16, v30
	v_and_b32_e32 v37, 0xffff0000, v30
	v_lshlrev_b32_e32 v30, 16, v31
	v_and_b32_e32 v31, 0xffff0000, v31
	v_pk_add_f32 v[22:23], v[22:23], v[28:29]
	v_pk_add_f32 v[20:21], v[20:21], v[34:35]
	v_pk_add_f32 v[28:29], v[18:19], v[30:31]
	v_pk_add_f32 v[30:31], v[16:17], v[36:37]
	v_mul_f32_e32 v16, v21, v21
	v_mul_f32_e32 v17, v23, v23
	v_mul_f32_e32 v18, v31, v31
	v_mul_f32_e32 v19, v29, v29
	v_fmac_f32_e32 v16, v20, v20
	v_fmac_f32_e32 v17, v22, v22
	v_fmac_f32_e32 v18, v30, v30
	v_fmac_f32_e32 v19, v28, v28
	v_add_f32_e32 v16, v16, v17
	v_add_f32_e32 v17, v18, v19
	v_add_f32_e32 v16, v16, v17
	v_add_f32_e32 v16, v40, v16
	v_mov_b32_e32 v17, v16
	s_nop 1
	v_permlane16_swap_b32_e32 v16, v17
	v_cvt_pk_bf16_f32 v18, v20, v21
	v_cvt_pk_bf16_f32 v19, v22, v23
	v_cvt_pk_bf16_f32 v20, v30, v31
	v_cvt_pk_bf16_f32 v21, v28, v29
	s_waitcnt lgkmcnt(0)
	v_add_f32_e32 v16, v16, v17
	v_mov_b32_e32 v17, v16
	s_nop 1
	v_permlane32_swap_b32_e32 v16, v17
	global_store_dwordx4 v[38:39], v[18:21], off offset:256
	s_and_saveexec_b64 s[46:47], vcc
	s_cbranch_execz .LBB0_1620
	s_waitcnt lgkmcnt(0)
	v_add_f32_e32 v18, v16, v17
	s_lshl_b32 s26, s14, 2
	v_lshlrev_b64 v[16:17], 6, v[32:33]
	s_ashr_i32 s27, s26, 31
	v_lshl_add_u64 v[16:17], s[12:13], 0, v[16:17]
	v_lshl_add_u64 v[16:17], s[26:27], 2, v[16:17]
	s_lshl_b32 s16, s60, 2
	v_lshl_add_u64 v[16:17], v[16:17], 0, s[16:17]
	global_store_dword v[16:17], v18, off
.LBB0_1620:
	s_or_b64 exec, exec, s[46:47]
	v_add_u32_e32 v16, 0xb0, v146
	s_waitcnt lgkmcnt(0)
	v_ashrrev_i32_e32 v17, 31, v16
	v_lshlrev_b64 v[18:19], 11, v[16:17]
	v_lshl_add_u64 v[18:19], s[20:21], 0, v[18:19]
	v_lshl_add_u64 v[22:23], v[144:145], 1, v[18:19]
	s_waitcnt vmcnt(22)
	v_mov_b32_e32 v18, v226
	v_mov_b32_e32 v19, v227
	v_mov_b32_e32 v20, v228
	v_mov_b32_e32 v21, v229
	v_lshlrev_b32_e32 v24, 16, v18
	v_and_b32_e32 v25, 0xffff0000, v18
	v_lshlrev_b32_e32 v18, 16, v19
	v_and_b32_e32 v19, 0xffff0000, v19
	v_lshlrev_b32_e32 v26, 16, v20
	v_and_b32_e32 v27, 0xffff0000, v20
	v_lshlrev_b32_e32 v20, 16, v21
	v_and_b32_e32 v21, 0xffff0000, v21
	v_pk_add_f32 v[18:19], v[14:15], v[18:19]
	v_pk_add_f32 v[24:25], v[12:13], v[24:25]
	v_pk_add_f32 v[20:21], v[10:11], v[20:21]
	v_pk_add_f32 v[26:27], v[8:9], v[26:27]
	v_cvt_pk_bf16_f32 v8, v24, v25
	v_cvt_pk_bf16_f32 v9, v18, v19
	v_mul_f32_e32 v25, v25, v25
	v_cvt_pk_bf16_f32 v10, v26, v27
	v_cvt_pk_bf16_f32 v11, v20, v21
	v_mul_f32_e32 v19, v19, v19
	v_mul_f32_e32 v27, v27, v27
	v_mul_f32_e32 v21, v21, v21
	v_fmac_f32_e32 v25, v24, v24
	v_fmac_f32_e32 v19, v18, v18
	v_fmac_f32_e32 v27, v26, v26
	v_fmac_f32_e32 v21, v20, v20
	v_add_f32_e32 v18, v25, v19
	v_add_f32_e32 v19, v27, v21
	v_add_f32_e32 v24, v18, v19
	global_store_dwordx4 v[22:23], v[8:11], off
	s_waitcnt vmcnt(22)
	v_mov_b32_e32 v12, v230
	v_mov_b32_e32 v13, v231
	v_mov_b32_e32 v14, v232
	v_mov_b32_e32 v15, v233
	v_lshlrev_b32_e32 v18, 16, v12
	v_and_b32_e32 v19, 0xffff0000, v12
	v_lshlrev_b32_e32 v12, 16, v13
	v_and_b32_e32 v13, 0xffff0000, v13
	v_lshlrev_b32_e32 v20, 16, v14
	v_and_b32_e32 v21, 0xffff0000, v14
	v_lshlrev_b32_e32 v14, 16, v15
	v_and_b32_e32 v15, 0xffff0000, v15
	v_pk_add_f32 v[6:7], v[6:7], v[12:13]
	v_pk_add_f32 v[4:5], v[4:5], v[18:19]
	v_pk_add_f32 v[12:13], v[2:3], v[14:15]
	v_pk_add_f32 v[14:15], v[0:1], v[20:21]
	v_mul_f32_e32 v0, v5, v5
	v_mul_f32_e32 v1, v7, v7
	v_mul_f32_e32 v2, v15, v15
	v_mul_f32_e32 v3, v13, v13
	v_fmac_f32_e32 v0, v4, v4
	v_fmac_f32_e32 v1, v6, v6
	v_fmac_f32_e32 v2, v14, v14
	v_fmac_f32_e32 v3, v12, v12
	v_add_f32_e32 v0, v0, v1
	v_add_f32_e32 v1, v2, v3
	v_add_f32_e32 v0, v0, v1
	v_add_f32_e32 v0, v24, v0
	v_mov_b32_e32 v1, v0
	s_nop 1
	v_permlane16_swap_b32_e32 v0, v1
	v_cvt_pk_bf16_f32 v2, v4, v5
	v_cvt_pk_bf16_f32 v3, v6, v7
	v_cvt_pk_bf16_f32 v4, v14, v15
	v_cvt_pk_bf16_f32 v5, v12, v13
	s_waitcnt lgkmcnt(0)
	v_add_f32_e32 v0, v0, v1
	v_mov_b32_e32 v1, v0
	s_nop 1
	v_permlane32_swap_b32_e32 v0, v1
	global_store_dwordx4 v[22:23], v[2:5], off offset:256
	s_and_saveexec_b64 s[46:47], vcc
	s_cbranch_execz .LBB0_1622
	s_waitcnt lgkmcnt(0)
	v_add_f32_e32 v2, v0, v1
	s_lshl_b32 s26, s14, 2
	v_lshlrev_b64 v[0:1], 6, v[16:17]
	s_ashr_i32 s27, s26, 31
	v_lshl_add_u64 v[0:1], s[12:13], 0, v[0:1]
	v_lshl_add_u64 v[0:1], s[26:27], 2, v[0:1]
	s_lshl_b32 s16, s60, 2
	v_lshl_add_u64 v[0:1], v[0:1], 0, s[16:17]
	global_store_dword v[0:1], v2, off

.LBB0_1934:
	v_mov_b32_e32 v156, v178
	v_mov_b32_e32 v164, v179
	s_lshl_b32 s27, s59, 8
	v_add_u32_e32 v185, s49, v156
	s_lshl_b32 s16, s26, 8
	v_add_u32_e32 v144, s27, v185
	s_or_b32 s16, s16, s50
	v_ashrrev_i32_e32 v145, 31, v144
	v_lshl_add_u32 v146, v164, 3, s16
	v_lshlrev_b64 v[148:149], 11, v[144:145]
	v_ashrrev_i32_e32 v147, 31, v146
	v_lshl_add_u64 v[148:149], s[14:15], 0, v[148:149]
	v_lshl_add_u64 v[152:153], v[146:147], 1, v[148:149]
	s_mov_b32 s90, 0x8000
	s_mov_b32 s91, 0
	s_mov_b32 s92, 0x28000
	s_mov_b32 s93, 0
	v_lshl_add_u64 v[254:255], v[152:153], 0, s[90:91]
	global_load_dwordx4 v[194:197], v[254:255], off
	global_load_dwordx4 v[198:201], v[254:255], off offset:256
	v_lshl_add_u64 v[254:255], v[254:255], 0, s[90:91]
	global_load_dwordx4 v[202:205], v[254:255], off
	global_load_dwordx4 v[206:209], v[254:255], off offset:256
	v_lshl_add_u64 v[254:255], v[254:255], 0, s[90:91]
	global_load_dwordx4 v[210:213], v[254:255], off
	global_load_dwordx4 v[214:217], v[254:255], off offset:256
	v_lshl_add_u64 v[254:255], v[254:255], 0, s[92:93]
	global_load_dwordx4 v[218:221], v[254:255], off
	global_load_dwordx4 v[226:229], v[254:255], off offset:256
	v_lshl_add_u64 v[254:255], v[254:255], 0, s[90:91]
	global_load_dwordx4 v[230:233], v[254:255], off
	global_load_dwordx4 v[234:237], v[254:255], off offset:256
	v_lshl_add_u64 v[254:255], v[254:255], 0, s[90:91]
	global_load_dwordx4 v[238:241], v[254:255], off
	global_load_dwordx4 v[242:245], v[254:255], off offset:256
	v_lshl_add_u64 v[254:255], v[254:255], 0, s[90:91]
	global_load_dwordx4 v[246:249], v[254:255], off
	global_load_dwordx4 v[180:183], v[254:255], off offset:256
	global_load_dwordx4 v[148:151], v[152:153], off
	s_nop 0
	global_load_dwordx4 v[152:155], v[152:153], off offset:256
	v_lshlrev_b32_e32 v156, 2, v156
	v_lshl_add_u32 v165, v164, 6, v156
	v_xor_b32_e32 v186, 64, v165
	v_xor_b32_e32 v187, 0x80, v165
	s_lshl_b32 s34, s26, 2
	v_cmp_eq_u32_e32 vcc, 0, v164
	s_ashr_i32 s35, s34, 31
	s_waitcnt vmcnt(0)
	v_lshlrev_b32_e32 v156, 16, v148
	v_and_b32_e32 v157, 0xffff0000, v148
	v_lshlrev_b32_e32 v148, 16, v149
	v_and_b32_e32 v149, 0xffff0000, v149
	v_lshlrev_b32_e32 v158, 16, v150
	v_and_b32_e32 v159, 0xffff0000, v150
	v_lshlrev_b32_e32 v150, 16, v151
	v_and_b32_e32 v151, 0xffff0000, v151
	v_lshlrev_b32_e32 v160, 16, v152
	v_and_b32_e32 v161, 0xffff0000, v152
	v_lshlrev_b32_e32 v152, 16, v153
	v_and_b32_e32 v153, 0xffff0000, v153
	v_lshlrev_b32_e32 v162, 16, v154
	v_and_b32_e32 v163, 0xffff0000, v154
	v_lshlrev_b32_e32 v154, 16, v155
	v_and_b32_e32 v155, 0xffff0000, v155
	v_pk_add_f32 v[126:127], v[126:127], v[148:149]
	v_pk_add_f32 v[124:125], v[124:125], v[156:157]
	v_pk_add_f32 v[122:123], v[122:123], v[150:151]
	v_pk_add_f32 v[120:121], v[120:121], v[158:159]
	v_pk_add_f32 v[118:119], v[118:119], v[152:153]
	v_pk_add_f32 v[116:117], v[116:117], v[160:161]
	v_pk_add_f32 v[114:115], v[114:115], v[154:155]
	v_pk_add_f32 v[112:113], v[112:113], v[162:163]
	v_mul_f32_e32 v148, v125, v125
	v_mul_f32_e32 v149, v127, v127
	v_mul_f32_e32 v150, v121, v121
	v_mul_f32_e32 v151, v123, v123
	v_mul_f32_e32 v152, v117, v117
	v_mul_f32_e32 v153, v119, v119
	v_mul_f32_e32 v154, v113, v113
	v_mul_f32_e32 v155, v115, v115
	v_fmac_f32_e32 v148, v124, v124
	v_fmac_f32_e32 v149, v126, v126
	v_fmac_f32_e32 v150, v120, v120
	v_fmac_f32_e32 v151, v122, v122
	v_fmac_f32_e32 v152, v116, v116
	v_fmac_f32_e32 v153, v118, v118
	v_fmac_f32_e32 v154, v112, v112
	v_fmac_f32_e32 v155, v114, v114
	v_add_f32_e32 v148, v148, v149
	v_add_f32_e32 v149, v150, v151
	v_add_f32_e32 v150, v152, v153
	v_add_f32_e32 v151, v154, v155
	v_add_f32_e32 v148, v148, v149
	v_add_f32_e32 v149, v150, v151
	v_add_f32_e32 v148, v148, v149
	v_mov_b32_e32 v149, v148
	s_nop 1
	v_permlane16_swap_b32_e32 v148, v149
	s_waitcnt lgkmcnt(0)
	v_add_f32_e32 v148, v148, v149
	v_mov_b32_e32 v149, v148
	s_nop 1
	v_permlane32_swap_b32_e32 v148, v149
	s_and_saveexec_b64 s[36:37], vcc
	s_cbranch_execz .LBB0_1936
	v_lshlrev_b64 v[150:151], 6, v[144:145]
	v_lshl_add_u64 v[150:151], s[12:13], 0, v[150:151]
	v_lshl_add_u64 v[150:151], s[34:35], 2, v[150:151]
	s_lshl_b32 s16, s48, 2
	v_lshl_add_u64 v[150:151], v[150:151], 0, s[16:17]
	s_waitcnt lgkmcnt(0)
	v_add_f32_e32 v148, v148, v149
	global_store_dword v[150:151], v148, off sc1
.LBB0_1936:
	s_or_b64 exec, exec, s[36:37]
	v_add_u32_e32 v148, 16, v144
	s_waitcnt lgkmcnt(0)
	v_ashrrev_i32_e32 v149, 31, v148
	v_lshlrev_b64 v[150:151], 11, v[148:149]
	v_lshl_add_u64 v[150:151], s[14:15], 0, v[150:151]
	v_lshl_add_u64 v[154:155], v[146:147], 1, v[150:151]
	s_nop 0
	s_waitcnt vmcnt(15)
	v_mov_b32_e32 v150, v194
	v_mov_b32_e32 v151, v195
	v_mov_b32_e32 v152, v196
	v_mov_b32_e32 v153, v197
	v_lshlrev_b32_e32 v158, 16, v150
	v_and_b32_e32 v159, 0xffff0000, v150
	v_lshlrev_b32_e32 v150, 16, v151
	v_and_b32_e32 v151, 0xffff0000, v151
	v_lshlrev_b32_e32 v160, 16, v152
	v_and_b32_e32 v161, 0xffff0000, v152
	v_lshlrev_b32_e32 v152, 16, v153
	v_and_b32_e32 v153, 0xffff0000, v153
	v_mov_b32_e32 v154, v198
	v_mov_b32_e32 v155, v199
	v_mov_b32_e32 v156, v200
	v_mov_b32_e32 v157, v201
	v_lshlrev_b32_e32 v162, 16, v154
	v_and_b32_e32 v163, 0xffff0000, v154
	v_lshlrev_b32_e32 v154, 16, v155
	v_and_b32_e32 v155, 0xffff0000, v155
	v_lshlrev_b32_e32 v164, 16, v156
	v_and_b32_e32 v165, 0xffff0000, v156
	v_lshlrev_b32_e32 v156, 16, v157
	v_and_b32_e32 v157, 0xffff0000, v157
	v_pk_add_f32 v[110:111], v[110:111], v[150:151]
	v_pk_add_f32 v[108:109], v[108:109], v[158:159]
	v_pk_add_f32 v[106:107], v[106:107], v[152:153]
	v_pk_add_f32 v[104:105], v[104:105], v[160:161]
	v_pk_add_f32 v[102:103], v[102:103], v[154:155]
	v_pk_add_f32 v[100:101], v[100:101], v[162:163]
	v_pk_add_f32 v[98:99], v[98:99], v[156:157]
	v_pk_add_f32 v[96:97], v[96:97], v[164:165]
	v_mul_f32_e32 v150, v109, v109
	v_mul_f32_e32 v151, v111, v111
	v_mul_f32_e32 v152, v105, v105
	v_mul_f32_e32 v153, v107, v107
	v_mul_f32_e32 v154, v101, v101
	v_mul_f32_e32 v155, v103, v103
	v_mul_f32_e32 v156, v97, v97
	v_mul_f32_e32 v157, v99, v99
	v_fmac_f32_e32 v150, v108, v108
	v_fmac_f32_e32 v151, v110, v110
	v_fmac_f32_e32 v152, v104, v104
	v_fmac_f32_e32 v153, v106, v106
	v_fmac_f32_e32 v154, v100, v100
	v_fmac_f32_e32 v155, v102, v102
	v_fmac_f32_e32 v156, v96, v96
	v_fmac_f32_e32 v157, v98, v98
	v_add_f32_e32 v150, v150, v151
	v_add_f32_e32 v151, v152, v153
	v_add_f32_e32 v152, v154, v155
	v_add_f32_e32 v153, v156, v157
	v_add_f32_e32 v150, v150, v151
	v_add_f32_e32 v151, v152, v153
	v_add_f32_e32 v150, v150, v151
	v_mov_b32_e32 v151, v150
	s_nop 1
	v_permlane16_swap_b32_e32 v150, v151
	s_waitcnt lgkmcnt(0)
	v_add_f32_e32 v150, v150, v151
	v_mov_b32_e32 v151, v150
	s_nop 1
	v_permlane32_swap_b32_e32 v150, v151
	s_and_saveexec_b64 s[36:37], vcc
	s_cbranch_execz .LBB0_1938
	v_lshlrev_b64 v[152:153], 6, v[148:149]
	v_lshl_add_u64 v[152:153], s[12:13], 0, v[152:153]
	v_lshl_add_u64 v[152:153], s[34:35], 2, v[152:153]
	s_lshl_b32 s16, s48, 2
	v_lshl_add_u64 v[152:153], v[152:153], 0, s[16:17]
	s_waitcnt lgkmcnt(0)
	v_add_f32_e32 v150, v150, v151
	global_store_dword v[152:153], v150, off sc1
.LBB0_1938:
	s_or_b64 exec, exec, s[36:37]
	v_add_u32_e32 v150, 32, v144
	s_waitcnt lgkmcnt(0)
	v_ashrrev_i32_e32 v151, 31, v150
	v_lshlrev_b64 v[152:153], 11, v[150:151]
	v_lshl_add_u64 v[152:153], s[14:15], 0, v[152:153]
	v_lshl_add_u64 v[156:157], v[146:147], 1, v[152:153]
	s_nop 0
	s_waitcnt vmcnt(15)
	v_mov_b32_e32 v152, v202
	v_mov_b32_e32 v153, v203
	v_mov_b32_e32 v154, v204
	v_mov_b32_e32 v155, v205
	v_lshlrev_b32_e32 v160, 16, v152
	v_and_b32_e32 v161, 0xffff0000, v152
	v_lshlrev_b32_e32 v152, 16, v153
	v_and_b32_e32 v153, 0xffff0000, v153
	v_lshlrev_b32_e32 v162, 16, v154
	v_and_b32_e32 v163, 0xffff0000, v154
	v_lshlrev_b32_e32 v154, 16, v155
	v_and_b32_e32 v155, 0xffff0000, v155
	v_mov_b32_e32 v156, v206
	v_mov_b32_e32 v157, v207
	v_mov_b32_e32 v158, v208
	v_mov_b32_e32 v159, v209
	v_lshlrev_b32_e32 v164, 16, v156
	v_and_b32_e32 v165, 0xffff0000, v156
	v_lshlrev_b32_e32 v156, 16, v157
	v_and_b32_e32 v157, 0xffff0000, v157
	v_lshlrev_b32_e32 v166, 16, v158
	v_and_b32_e32 v167, 0xffff0000, v158
	v_lshlrev_b32_e32 v158, 16, v159
	v_and_b32_e32 v159, 0xffff0000, v159
	v_pk_add_f32 v[94:95], v[94:95], v[152:153]
	v_pk_add_f32 v[92:93], v[92:93], v[160:161]
	v_pk_add_f32 v[90:91], v[90:91], v[154:155]
	v_pk_add_f32 v[88:89], v[88:89], v[162:163]
	v_pk_add_f32 v[86:87], v[86:87], v[156:157]
	v_pk_add_f32 v[84:85], v[84:85], v[164:165]
	v_pk_add_f32 v[82:83], v[82:83], v[158:159]
	v_pk_add_f32 v[80:81], v[80:81], v[166:167]
	v_mul_f32_e32 v152, v93, v93
	v_mul_f32_e32 v153, v95, v95
	v_mul_f32_e32 v154, v89, v89
	v_mul_f32_e32 v155, v91, v91
	v_mul_f32_e32 v156, v85, v85
	v_mul_f32_e32 v157, v87, v87
	v_mul_f32_e32 v158, v81, v81
	v_mul_f32_e32 v159, v83, v83
	v_fmac_f32_e32 v152, v92, v92
	v_fmac_f32_e32 v153, v94, v94
	v_fmac_f32_e32 v154, v88, v88
	v_fmac_f32_e32 v155, v90, v90
	v_fmac_f32_e32 v156, v84, v84
	v_fmac_f32_e32 v157, v86, v86
	v_fmac_f32_e32 v158, v80, v80
	v_fmac_f32_e32 v159, v82, v82
	v_add_f32_e32 v152, v152, v153
	v_add_f32_e32 v153, v154, v155
	v_add_f32_e32 v154, v156, v157
	v_add_f32_e32 v155, v158, v159
	v_add_f32_e32 v152, v152, v153
	v_add_f32_e32 v153, v154, v155
	v_add_f32_e32 v152, v152, v153
	v_mov_b32_e32 v153, v152
	s_nop 1
	v_permlane16_swap_b32_e32 v152, v153
	s_waitcnt lgkmcnt(0)
	v_add_f32_e32 v152, v152, v153
	v_mov_b32_e32 v153, v152
	s_nop 1
	v_permlane32_swap_b32_e32 v152, v153
	s_and_saveexec_b64 s[36:37], vcc
	s_cbranch_execz .LBB0_1940
	v_lshlrev_b64 v[154:155], 6, v[150:151]
	v_lshl_add_u64 v[154:155], s[12:13], 0, v[154:155]
	v_lshl_add_u64 v[154:155], s[34:35], 2, v[154:155]
	s_lshl_b32 s16, s48, 2
	v_lshl_add_u64 v[154:155], v[154:155], 0, s[16:17]
	s_waitcnt lgkmcnt(0)
	v_add_f32_e32 v152, v152, v153
	global_store_dword v[154:155], v152, off sc1
.LBB0_1940:
	s_or_b64 exec, exec, s[36:37]
	v_add_u32_e32 v152, 48, v144
	s_waitcnt lgkmcnt(0)
	v_ashrrev_i32_e32 v153, 31, v152
	v_lshlrev_b64 v[154:155], 11, v[152:153]
	v_lshl_add_u64 v[154:155], s[14:15], 0, v[154:155]
	v_lshl_add_u64 v[158:159], v[146:147], 1, v[154:155]
	s_nop 0
	s_waitcnt vmcnt(15)
	v_mov_b32_e32 v154, v210
	v_mov_b32_e32 v155, v211
	v_mov_b32_e32 v156, v212
	v_mov_b32_e32 v157, v213
	v_lshlrev_b32_e32 v162, 16, v154
	v_and_b32_e32 v163, 0xffff0000, v154
	v_lshlrev_b32_e32 v154, 16, v155
	v_and_b32_e32 v155, 0xffff0000, v155
	v_lshlrev_b32_e32 v164, 16, v156
	v_and_b32_e32 v165, 0xffff0000, v156
	v_lshlrev_b32_e32 v156, 16, v157
	v_and_b32_e32 v157, 0xffff0000, v157
	v_mov_b32_e32 v158, v214
	v_mov_b32_e32 v159, v215
	v_mov_b32_e32 v160, v216
	v_mov_b32_e32 v161, v217
	v_lshlrev_b32_e32 v166, 16, v158
	v_and_b32_e32 v167, 0xffff0000, v158
	v_lshlrev_b32_e32 v158, 16, v159
	v_and_b32_e32 v159, 0xffff0000, v159
	v_lshlrev_b32_e32 v168, 16, v160
	v_and_b32_e32 v169, 0xffff0000, v160
	v_lshlrev_b32_e32 v160, 16, v161
	v_and_b32_e32 v161, 0xffff0000, v161
	v_pk_add_f32 v[78:79], v[78:79], v[154:155]
	v_pk_add_f32 v[76:77], v[76:77], v[162:163]
	v_pk_add_f32 v[74:75], v[74:75], v[156:157]
	v_pk_add_f32 v[72:73], v[72:73], v[164:165]
	v_pk_add_f32 v[70:71], v[70:71], v[158:159]
	v_pk_add_f32 v[68:69], v[68:69], v[166:167]
	v_pk_add_f32 v[66:67], v[66:67], v[160:161]
	v_pk_add_f32 v[64:65], v[64:65], v[168:169]
	v_mul_f32_e32 v154, v77, v77
	v_mul_f32_e32 v155, v79, v79
	v_mul_f32_e32 v156, v73, v73
	v_mul_f32_e32 v157, v75, v75
	v_mul_f32_e32 v158, v69, v69
	v_mul_f32_e32 v159, v71, v71
	v_mul_f32_e32 v160, v65, v65
	v_mul_f32_e32 v161, v67, v67
	v_fmac_f32_e32 v154, v76, v76
	v_fmac_f32_e32 v155, v78, v78
	v_fmac_f32_e32 v156, v72, v72
	v_fmac_f32_e32 v157, v74, v74
	v_fmac_f32_e32 v158, v68, v68
	v_fmac_f32_e32 v159, v70, v70
	v_fmac_f32_e32 v160, v64, v64
	v_fmac_f32_e32 v161, v66, v66
	v_add_f32_e32 v154, v154, v155
	v_add_f32_e32 v155, v156, v157
	v_add_f32_e32 v156, v158, v159
	v_add_f32_e32 v157, v160, v161
	v_add_f32_e32 v154, v154, v155
	v_add_f32_e32 v155, v156, v157
	v_add_f32_e32 v154, v154, v155
	v_mov_b32_e32 v155, v154
	s_nop 1
	v_permlane16_swap_b32_e32 v154, v155
	s_waitcnt lgkmcnt(0)
	v_add_f32_e32 v154, v154, v155
	v_mov_b32_e32 v155, v154
	s_nop 1
	v_permlane32_swap_b32_e32 v154, v155
	s_and_saveexec_b64 s[36:37], vcc
	s_cbranch_execz .LBB0_1942
	v_lshlrev_b64 v[156:157], 6, v[152:153]
	v_lshl_add_u64 v[156:157], s[12:13], 0, v[156:157]
	v_lshl_add_u64 v[156:157], s[34:35], 2, v[156:157]
	s_lshl_b32 s16, s48, 2
	v_lshl_add_u64 v[156:157], v[156:157], 0, s[16:17]
	s_waitcnt lgkmcnt(0)
	v_add_f32_e32 v154, v154, v155
	global_store_dword v[156:157], v154, off sc1
.LBB0_1942:
	s_or_b64 exec, exec, s[36:37]
	v_add_u32_e32 v154, 0x80, v144
	s_waitcnt lgkmcnt(0)
	v_ashrrev_i32_e32 v155, 31, v154
	v_lshlrev_b64 v[156:157], 11, v[154:155]
	v_lshl_add_u64 v[156:157], s[14:15], 0, v[156:157]
	v_lshl_add_u64 v[160:161], v[146:147], 1, v[156:157]
	s_nop 0
	s_waitcnt vmcnt(15)
	v_mov_b32_e32 v156, v218
	v_mov_b32_e32 v157, v219
	v_mov_b32_e32 v158, v220
	v_mov_b32_e32 v159, v221
	v_lshlrev_b32_e32 v164, 16, v156
	v_and_b32_e32 v165, 0xffff0000, v156
	v_lshlrev_b32_e32 v156, 16, v157
	v_and_b32_e32 v157, 0xffff0000, v157
	v_lshlrev_b32_e32 v166, 16, v158
	v_and_b32_e32 v167, 0xffff0000, v158
	v_lshlrev_b32_e32 v158, 16, v159
	v_and_b32_e32 v159, 0xffff0000, v159
	v_mov_b32_e32 v160, v226
	v_mov_b32_e32 v161, v227
	v_mov_b32_e32 v162, v228
	v_mov_b32_e32 v163, v229
	v_lshlrev_b32_e32 v168, 16, v160
	v_and_b32_e32 v169, 0xffff0000, v160
	v_lshlrev_b32_e32 v160, 16, v161
	v_and_b32_e32 v161, 0xffff0000, v161
	v_lshlrev_b32_e32 v170, 16, v162
	v_and_b32_e32 v171, 0xffff0000, v162
	v_lshlrev_b32_e32 v162, 16, v163
	v_and_b32_e32 v163, 0xffff0000, v163
	v_pk_add_f32 v[62:63], v[62:63], v[156:157]
	v_pk_add_f32 v[60:61], v[60:61], v[164:165]
	v_pk_add_f32 v[58:59], v[58:59], v[158:159]
	v_pk_add_f32 v[56:57], v[56:57], v[166:167]
	v_pk_add_f32 v[54:55], v[54:55], v[160:161]
	v_pk_add_f32 v[52:53], v[52:53], v[168:169]
	v_pk_add_f32 v[50:51], v[50:51], v[162:163]
	v_pk_add_f32 v[48:49], v[48:49], v[170:171]
	v_mul_f32_e32 v156, v61, v61
	v_mul_f32_e32 v157, v63, v63
	v_mul_f32_e32 v158, v57, v57
	v_mul_f32_e32 v159, v59, v59
	v_mul_f32_e32 v160, v53, v53
	v_mul_f32_e32 v161, v55, v55
	v_mul_f32_e32 v162, v49, v49
	v_mul_f32_e32 v163, v51, v51
	v_fmac_f32_e32 v156, v60, v60
	v_fmac_f32_e32 v157, v62, v62
	v_fmac_f32_e32 v158, v56, v56
	v_fmac_f32_e32 v159, v58, v58
	v_fmac_f32_e32 v160, v52, v52
	v_fmac_f32_e32 v161, v54, v54
	v_fmac_f32_e32 v162, v48, v48
	v_fmac_f32_e32 v163, v50, v50
	v_add_f32_e32 v156, v156, v157
	v_add_f32_e32 v157, v158, v159
	v_add_f32_e32 v158, v160, v161
	v_add_f32_e32 v159, v162, v163
	v_add_f32_e32 v156, v156, v157
	v_add_f32_e32 v157, v158, v159
	v_add_f32_e32 v156, v156, v157
	v_mov_b32_e32 v157, v156
	s_nop 1
	v_permlane16_swap_b32_e32 v156, v157
	s_waitcnt lgkmcnt(0)
	v_add_f32_e32 v156, v156, v157
	v_mov_b32_e32 v157, v156
	s_nop 1
	v_permlane32_swap_b32_e32 v156, v157
	s_and_saveexec_b64 s[36:37], vcc
	s_cbranch_execz .LBB0_1944
	v_lshlrev_b64 v[158:159], 6, v[154:155]
	v_lshl_add_u64 v[158:159], s[12:13], 0, v[158:159]
	v_lshl_add_u64 v[158:159], s[34:35], 2, v[158:159]
	s_lshl_b32 s16, s48, 2
	v_lshl_add_u64 v[158:159], v[158:159], 0, s[16:17]
	s_waitcnt lgkmcnt(0)
	v_add_f32_e32 v156, v156, v157
	global_store_dword v[158:159], v156, off sc1
.LBB0_1944:
	s_or_b64 exec, exec, s[36:37]
	v_add_u32_e32 v156, 0x90, v144
	s_waitcnt lgkmcnt(0)
	v_ashrrev_i32_e32 v157, 31, v156
	v_lshlrev_b64 v[158:159], 11, v[156:157]
	v_lshl_add_u64 v[158:159], s[14:15], 0, v[158:159]
	v_lshl_add_u64 v[162:163], v[146:147], 1, v[158:159]
	s_nop 0
	s_waitcnt vmcnt(15)
	v_mov_b32_e32 v158, v230
	v_mov_b32_e32 v159, v231
	v_mov_b32_e32 v160, v232
	v_mov_b32_e32 v161, v233
	v_lshlrev_b32_e32 v166, 16, v158
	v_and_b32_e32 v167, 0xffff0000, v158
	v_lshlrev_b32_e32 v158, 16, v159
	v_and_b32_e32 v159, 0xffff0000, v159
	v_lshlrev_b32_e32 v168, 16, v160
	v_and_b32_e32 v169, 0xffff0000, v160
	v_lshlrev_b32_e32 v160, 16, v161
	v_and_b32_e32 v161, 0xffff0000, v161
	v_mov_b32_e32 v162, v234
	v_mov_b32_e32 v163, v235
	v_mov_b32_e32 v164, v236
	v_mov_b32_e32 v165, v237
	v_lshlrev_b32_e32 v170, 16, v162
	v_and_b32_e32 v171, 0xffff0000, v162
	v_lshlrev_b32_e32 v162, 16, v163
	v_and_b32_e32 v163, 0xffff0000, v163
	v_lshlrev_b32_e32 v172, 16, v164
	v_and_b32_e32 v173, 0xffff0000, v164
	v_lshlrev_b32_e32 v164, 16, v165
	v_and_b32_e32 v165, 0xffff0000, v165
	v_pk_add_f32 v[46:47], v[46:47], v[158:159]
	v_pk_add_f32 v[44:45], v[44:45], v[166:167]
	v_pk_add_f32 v[42:43], v[42:43], v[160:161]
	v_pk_add_f32 v[40:41], v[40:41], v[168:169]
	v_pk_add_f32 v[38:39], v[38:39], v[162:163]
	v_pk_add_f32 v[36:37], v[36:37], v[170:171]
	v_pk_add_f32 v[34:35], v[34:35], v[164:165]
	v_pk_add_f32 v[32:33], v[32:33], v[172:173]
	v_mul_f32_e32 v158, v45, v45
	v_mul_f32_e32 v159, v47, v47
	v_mul_f32_e32 v160, v41, v41
	v_mul_f32_e32 v161, v43, v43
	v_mul_f32_e32 v162, v37, v37
	v_mul_f32_e32 v163, v39, v39
	v_mul_f32_e32 v164, v33, v33
	v_mul_f32_e32 v165, v35, v35
	v_fmac_f32_e32 v158, v44, v44
	v_fmac_f32_e32 v159, v46, v46
	v_fmac_f32_e32 v160, v40, v40
	v_fmac_f32_e32 v161, v42, v42
	v_fmac_f32_e32 v162, v36, v36
	v_fmac_f32_e32 v163, v38, v38
	v_fmac_f32_e32 v164, v32, v32
	v_fmac_f32_e32 v165, v34, v34
	v_add_f32_e32 v158, v158, v159
	v_add_f32_e32 v159, v160, v161
	v_add_f32_e32 v160, v162, v163
	v_add_f32_e32 v161, v164, v165
	v_add_f32_e32 v158, v158, v159
	v_add_f32_e32 v159, v160, v161
	v_add_f32_e32 v158, v158, v159
	v_mov_b32_e32 v159, v158
	s_nop 1
	v_permlane16_swap_b32_e32 v158, v159
	s_waitcnt lgkmcnt(0)
	v_add_f32_e32 v158, v158, v159
	v_mov_b32_e32 v159, v158
	s_nop 1
	v_permlane32_swap_b32_e32 v158, v159
	s_and_saveexec_b64 s[36:37], vcc
	s_cbranch_execz .LBB0_1946
	v_lshlrev_b64 v[160:161], 6, v[156:157]
	v_lshl_add_u64 v[160:161], s[12:13], 0, v[160:161]
	v_lshl_add_u64 v[160:161], s[34:35], 2, v[160:161]
	s_lshl_b32 s16, s48, 2
	v_lshl_add_u64 v[160:161], v[160:161], 0, s[16:17]
	s_waitcnt lgkmcnt(0)
	v_add_f32_e32 v158, v158, v159
	global_store_dword v[160:161], v158, off sc1
.LBB0_1946:
	s_or_b64 exec, exec, s[36:37]
	v_add_u32_e32 v158, 0xa0, v144
	s_waitcnt lgkmcnt(0)
	v_ashrrev_i32_e32 v159, 31, v158
	v_lshlrev_b64 v[160:161], 11, v[158:159]
	v_lshl_add_u64 v[160:161], s[14:15], 0, v[160:161]
	v_lshl_add_u64 v[164:165], v[146:147], 1, v[160:161]
	s_nop 0
	s_waitcnt vmcnt(15)
	v_mov_b32_e32 v160, v238
	v_mov_b32_e32 v161, v239
	v_mov_b32_e32 v162, v240
	v_mov_b32_e32 v163, v241
	v_lshlrev_b32_e32 v168, 16, v160
	v_and_b32_e32 v169, 0xffff0000, v160
	v_lshlrev_b32_e32 v160, 16, v161
	v_and_b32_e32 v161, 0xffff0000, v161
	v_lshlrev_b32_e32 v170, 16, v162
	v_and_b32_e32 v171, 0xffff0000, v162
	v_lshlrev_b32_e32 v162, 16, v163
	v_and_b32_e32 v163, 0xffff0000, v163
	v_mov_b32_e32 v164, v242
	v_mov_b32_e32 v165, v243
	v_mov_b32_e32 v166, v244
	v_mov_b32_e32 v167, v245
	v_lshlrev_b32_e32 v172, 16, v164
	v_and_b32_e32 v173, 0xffff0000, v164
	v_lshlrev_b32_e32 v164, 16, v165
	v_and_b32_e32 v165, 0xffff0000, v165
	v_lshlrev_b32_e32 v174, 16, v166
	v_and_b32_e32 v175, 0xffff0000, v166
	v_lshlrev_b32_e32 v166, 16, v167
	v_and_b32_e32 v167, 0xffff0000, v167
	v_pk_add_f32 v[30:31], v[30:31], v[160:161]
	v_pk_add_f32 v[28:29], v[28:29], v[168:169]
	v_pk_add_f32 v[26:27], v[26:27], v[162:163]
	v_pk_add_f32 v[24:25], v[24:25], v[170:171]
	v_pk_add_f32 v[22:23], v[22:23], v[164:165]
	v_pk_add_f32 v[20:21], v[20:21], v[172:173]
	v_pk_add_f32 v[18:19], v[18:19], v[166:167]
	v_pk_add_f32 v[16:17], v[16:17], v[174:175]
	v_mul_f32_e32 v160, v29, v29
	v_mul_f32_e32 v161, v31, v31
	v_mul_f32_e32 v162, v25, v25
	v_mul_f32_e32 v163, v27, v27
	v_mul_f32_e32 v164, v21, v21
	v_mul_f32_e32 v165, v23, v23
	v_mul_f32_e32 v166, v17, v17
	v_mul_f32_e32 v167, v19, v19
	v_fmac_f32_e32 v160, v28, v28
	v_fmac_f32_e32 v161, v30, v30
	v_fmac_f32_e32 v162, v24, v24
	v_fmac_f32_e32 v163, v26, v26
	v_fmac_f32_e32 v164, v20, v20
	v_fmac_f32_e32 v165, v22, v22
	v_fmac_f32_e32 v166, v16, v16
	v_fmac_f32_e32 v167, v18, v18
	v_add_f32_e32 v160, v160, v161
	v_add_f32_e32 v161, v162, v163
	v_add_f32_e32 v162, v164, v165
	v_add_f32_e32 v163, v166, v167
	v_add_f32_e32 v160, v160, v161
	v_add_f32_e32 v161, v162, v163
	v_add_f32_e32 v160, v160, v161
	v_mov_b32_e32 v161, v160
	s_nop 1
	v_permlane16_swap_b32_e32 v160, v161
	s_waitcnt lgkmcnt(0)
	v_add_f32_e32 v160, v160, v161
	v_mov_b32_e32 v161, v160
	s_nop 1
	v_permlane32_swap_b32_e32 v160, v161
	s_and_saveexec_b64 s[36:37], vcc
	s_cbranch_execz .LBB0_1948
	v_lshlrev_b64 v[162:163], 6, v[158:159]
	v_lshl_add_u64 v[162:163], s[12:13], 0, v[162:163]
	v_lshl_add_u64 v[162:163], s[34:35], 2, v[162:163]
	s_lshl_b32 s16, s48, 2
	v_lshl_add_u64 v[162:163], v[162:163], 0, s[16:17]
	s_waitcnt lgkmcnt(0)
	v_add_f32_e32 v160, v160, v161
	global_store_dword v[162:163], v160, off sc1
.LBB0_1948:
	s_or_b64 exec, exec, s[36:37]
	v_add_u32_e32 v160, 0xb0, v144
	s_waitcnt lgkmcnt(0)
	v_ashrrev_i32_e32 v161, 31, v160
	v_lshlrev_b64 v[162:163], 11, v[160:161]
	v_lshl_add_u64 v[162:163], s[14:15], 0, v[162:163]
	v_lshl_add_u64 v[166:167], v[146:147], 1, v[162:163]
	s_nop 0
	s_waitcnt vmcnt(15)
	v_mov_b32_e32 v162, v246
	v_mov_b32_e32 v163, v247
	v_mov_b32_e32 v164, v248
	v_mov_b32_e32 v165, v249
	v_lshlrev_b32_e32 v170, 16, v162
	v_and_b32_e32 v171, 0xffff0000, v162
	v_lshlrev_b32_e32 v162, 16, v163
	v_and_b32_e32 v163, 0xffff0000, v163
	v_lshlrev_b32_e32 v172, 16, v164
	v_and_b32_e32 v173, 0xffff0000, v164
	v_lshlrev_b32_e32 v164, 16, v165
	v_and_b32_e32 v165, 0xffff0000, v165
	v_mov_b32_e32 v166, v180
	v_mov_b32_e32 v167, v181
	v_mov_b32_e32 v168, v182
	v_mov_b32_e32 v169, v183
	v_lshlrev_b32_e32 v188, 16, v166
	v_and_b32_e32 v189, 0xffff0000, v166
	v_lshlrev_b32_e32 v166, 16, v167
	v_and_b32_e32 v167, 0xffff0000, v167
	v_lshlrev_b32_e32 v190, 16, v168
	v_and_b32_e32 v191, 0xffff0000, v168
	v_lshlrev_b32_e32 v192, 16, v169
	v_and_b32_e32 v193, 0xffff0000, v169
	v_pk_add_f32 v[174:175], v[14:15], v[162:163]
	v_pk_add_f32 v[176:177], v[12:13], v[170:171]
	v_pk_add_f32 v[170:171], v[10:11], v[164:165]
	v_pk_add_f32 v[172:173], v[8:9], v[172:173]
	v_pk_add_f32 v[164:165], v[6:7], v[166:167]
	v_pk_add_f32 v[168:169], v[4:5], v[188:189]
	v_pk_add_f32 v[162:163], v[2:3], v[192:193]
	v_pk_add_f32 v[166:167], v[0:1], v[190:191]
	v_mul_f32_e32 v0, v177, v177
	v_mul_f32_e32 v1, v175, v175
	v_mul_f32_e32 v2, v173, v173
	v_mul_f32_e32 v3, v171, v171
	v_mul_f32_e32 v4, v169, v169
	v_mul_f32_e32 v5, v165, v165
	v_mul_f32_e32 v6, v167, v167
	v_mul_f32_e32 v7, v163, v163
	v_fmac_f32_e32 v0, v176, v176
	v_fmac_f32_e32 v1, v174, v174
	v_fmac_f32_e32 v2, v172, v172
	v_fmac_f32_e32 v3, v170, v170
	v_fmac_f32_e32 v4, v168, v168
	v_fmac_f32_e32 v5, v164, v164
	v_fmac_f32_e32 v6, v166, v166
	v_fmac_f32_e32 v7, v162, v162
	v_add_f32_e32 v0, v0, v1
	v_add_f32_e32 v1, v2, v3
	v_add_f32_e32 v2, v4, v5
	v_add_f32_e32 v3, v6, v7
	v_add_f32_e32 v0, v0, v1
	v_add_f32_e32 v1, v2, v3
	v_add_f32_e32 v0, v0, v1
	v_mov_b32_e32 v1, v0
	s_nop 1
	v_permlane16_swap_b32_e32 v0, v1
	s_waitcnt lgkmcnt(0)
	v_add_f32_e32 v0, v0, v1
	v_mov_b32_e32 v1, v0
	s_nop 1
	v_permlane32_swap_b32_e32 v0, v1
	s_and_saveexec_b64 s[36:37], vcc
	s_cbranch_execz .LBB0_1950
	v_lshlrev_b64 v[2:3], 6, v[160:161]
	v_lshl_add_u64 v[2:3], s[12:13], 0, v[2:3]
	v_lshl_add_u64 v[2:3], s[34:35], 2, v[2:3]
	s_lshl_b32 s16, s48, 2
	v_lshl_add_u64 v[2:3], v[2:3], 0, s[16:17]
	s_waitcnt lgkmcnt(0)
	v_add_f32_e32 v0, v0, v1
	global_store_dword v[2:3], v0, off sc1
